# rwkv scan step loop rewritten: 4 waves x 8 rows, 2 rows packed per lane, folded 5-op DPP reduce, LDS prefetch one step ahead
# speedup vs baseline: 1.0780x; 1.0765x over previous
; __device__ __forceinline__ void phase_rwkv_scan(const Fr& F, int jr) {
;     ...
;     for (int task = bxcd; task < 256; task += gridDim.x) {
;         const int half = task & 1, h = (task >> 1) & 15, b = (task >> 5) & 3, s = task >> 7;
;         bf16* Yb = F.R(s);
;         const float* w0 = F.a->in[9] + (size_t)(jr * 2 + s) * D + h * 64; const float* a0 = F.a->in[12] + (size_t)(jr * 2 + s) * D + h * 64;
;         const float* kkw = F.a->in[15] + (size_t)jr * D + h * 64; const float* kaw = F.a->in[16] + (size_t)jr * D + h * 64;
;         f32x2 S01 = {0.f, 0.f}, S23 = {0.f, 0.f};
;         const int ks = 4 * l15, rloc = 4 * wave + lq;
;         const int pt = wave & 3, ht0 = (wave >> 2) * 2;
;         const int p1 = pt * 16 + l15;
;         const int p2 = tid >> 3, j8 = tid & 7, hk0 = 8 * j8;
;         bf16x8 Bw[2][2], Ba[2][2]; float w0v[2], a0v[2];
; #pragma unroll
;         for (int hh = 0; hh < 2; ++hh) { const int hk = (ht0 + hh) * 16 + l15, e = h * 64 + hk; w0v[hh] = w0[hk]; a0v[hh] = a0[hk];
; #pragma unroll
;             for (int kst = 0; kst < 2; ++kst) { Bw[hh][kst] = *(const bf16x8*)(L2T + ((size_t)s * D + e) * 64 + 32 * kst + 8 * lq); Ba[hh][kst] = *(const bf16x8*)(L2T + ((size_t)(2 + s) * D + e) * 64 + 32 * kst + 8 * lq); } }
;         float kkc[8], kac[8], rkc[8];
; #pragma unroll
;         for (int i = 0; i < 8; ++i) { kkc[i] = kkw[hk0 + i]; kac[i] = kaw[hk0 + i]; rkc[i] = F.a->in[17][(size_t)jr * D + h * 64 + hk0 + i]; }
;         float* Bon = (float*)(F.ws + OFF_R0 + 6 * RSZ + 16 * MiB);
;         bf16x8 Aw[2], Aa[2]; u32x4 kw, rw; u32x2 vw;
;         {   const size_t row1 = (size_t)b * TB + tokof(s, p1), row2 = (size_t)b * TB + tokof(s, p2);
; #pragma unroll
;             for (int kst = 0; kst < 2; ++kst) { Aw[kst] = *(const bf16x8*)(LM + row1 * 256 + 64 * s + 32 * kst + 8 * lq); Aa[kst] = *(const bf16x8*)(LM + row1 * 256 + 128 + 64 * s + 32 * kst + 8 * lq); }
;             kw = *(const u32x4*)(Kb + row2 * D + h * 64 + hk0); rw = *(const u32x4*)(Rb + row2 * D + h * 64 + hk0); vw = *(const u32x2*)(Vb + row2 * D + h * 64 + 32 * half + 4 * j8); }
;     ...
;                 float* Ypw = Yp + wave * 1024;
;                 unsigned a1 = (unsigned)(size_t)(__attribute__((address_space(3))) float*)(Wv + ks), a2 = (unsigned)(size_t)(__attribute__((address_space(3))) float*)(Rr + ks),
.LBB0_555:
	s_ashr_i32 s8, s3, 7
	s_ashr_i32 s9, s8, 31
	s_bfe_u32 s60, s3, 0x40001
	s_lshl_b64 s[6:7], s[8:9], 12
	s_add_u32 s10, s24, s6
	s_addc_u32 s11, s25, s7
	s_lshl_b32 s58, s60, 6
	s_lshl_b32 s22, s60, 8
	s_add_u32 s10, s10, s22
	s_addc_u32 s11, s11, 0
	s_add_u32 s6, s40, s6
	s_addc_u32 s7, s41, s7
	s_add_u32 s6, s6, s22
	s_addc_u32 s7, s7, 0
	s_lshl_b64 s[46:47], s[8:9], 17
	v_lshl_add_u64 v[16:17], v[124:125], 0, s[46:47]
	v_add_u32_e32 v122, s58, v138
	v_lshl_add_u64 v[18:19], v[16:17], 0, s[44:45]
	v_lshlrev_b64 v[0:1], 7, v[122:123]
	v_lshlrev_b32_e32 v20, 2, v138
	v_lshl_add_u64 v[4:5], v[16:17], 0, v[0:1]
	v_lshl_add_u64 v[12:13], v[18:19], 0, v[0:1]
	s_mul_i32 s57, s8, 0x2200000
	global_load_dwordx4 v[0:3], v[4:5], off
	s_nop 0
	global_load_dwordx4 v[4:7], v[4:5], off offset:64
	s_nop 0
	global_load_dwordx4 v[8:11], v[12:13], off
	s_nop 0
	global_load_dwordx4 v[12:15], v[12:13], off offset:64
	s_nop 0
	global_load_dword v193, v20, s[10:11]
	global_load_dword v194, v20, s[6:7]
	global_load_dword v195, v20, s[6:7] offset:64
	global_load_dword v196, v20, s[10:11] offset:64
	s_bfe_u32 s6, s3, 0x20005
	s_mul_hi_i32 s56, s8, 0x2200000
	s_add_u32 s61, s48, s57
	s_addc_u32 s62, s49, s56
	s_cmpk_lt_u32 s3, 0x80
	v_lshl_add_u64 v[44:45], v[140:141], 0, s[22:23]
	v_lshl_add_u64 v[52:53], v[142:143], 0, s[22:23]
	s_mul_i32 s22, s6, 0x1100
	s_cselect_b64 s[6:7], -1, 0
	s_waitcnt vmcnt(0)
	v_cndmask_b32_e64 v56, v135, v121, s[6:7]
	v_add_u32_e32 v122, s58, v177
	v_or_b32_e32 v56, s22, v56
	v_cndmask_b32_e64 v72, v139, v129, s[6:7]
	s_lshl_b32 s8, s8, 6
	v_lshlrev_b64 v[20:21], 7, v[122:123]
	v_or_b32_e32 v32, s58, v120
	v_lshlrev_b32_e32 v122, 9, v56
	s_ashr_i32 s9, s8, 31
	v_or_b32_e32 v72, s22, v72
	v_lshl_add_u64 v[22:23], v[16:17], 0, v[20:21]
	v_lshl_add_u64 v[28:29], v[18:19], 0, v[20:21]
	v_lshlrev_b32_e32 v36, 2, v32
	v_lshl_add_u64 v[56:57], s[20:21], 0, v[122:123]
	s_lshl_b64 s[10:11], s[8:9], 1
	v_lshlrev_b32_e32 v122, 11, v72
	global_load_dwordx4 v[16:19], v[22:23], off
	s_nop 0
	global_load_dwordx4 v[20:23], v[22:23], off offset:64
	s_nop 0
	global_load_dwordx4 v[24:27], v[28:29], off
	s_nop 0
	global_load_dwordx4 v[28:31], v[28:29], off offset:64
	s_nop 0
	global_load_dwordx4 v[32:35], v36, s[42:43]
	s_nop 0
	global_load_dwordx4 v[36:39], v36, s[42:43] offset:16
	s_nop 0
	global_load_dwordx4 v[40:43], v[44:45], off offset:16
	s_nop 0
	global_load_dwordx4 v[44:47], v[44:45], off
	s_nop 0
	global_load_dwordx4 v[48:51], v[52:53], off offset:16
	s_nop 0
	global_load_dwordx4 v[52:55], v[52:53], off
	v_lshl_add_u64 v[56:57], v[56:57], 0, s[10:11]
	v_mov_b32_e32 v147, v123
	s_lshl_b32 s56, s60, 7
	s_mov_b32 s57, s23
	v_lshl_add_u64 v[80:81], s[18:19], 0, v[122:123]
	s_lshl_b32 s8, s3, 6
	v_lshl_add_u64 v[68:69], v[56:57], 0, v[146:147]
	v_lshl_add_u64 v[72:73], s[16:17], 0, v[122:123]
	v_lshl_add_u64 v[76:77], s[14:15], 0, v[122:123]
	v_lshl_add_u64 v[80:81], v[80:81], 0, s[56:57]
	s_and_b32 s58, s8, 64
	s_mov_b32 s59, s23
	global_load_dwordx4 v[56:59], v[68:69], off
	global_load_dwordx4 v[60:63], v[68:69], off offset:64
	global_load_dwordx4 v[64:67], v[68:69], off offset:256
	s_nop 0
	global_load_dwordx4 v[68:71], v[68:69], off offset:320
	v_lshl_add_u64 v[72:73], v[72:73], 0, s[56:57]
	v_lshlrev_b32_e32 v74, 1, v120
	v_mov_b32_e32 v75, v123
	v_lshl_add_u64 v[76:77], v[76:77], 0, s[56:57]
	v_lshl_add_u64 v[80:81], v[80:81], 0, s[58:59]
	v_mov_b32_e32 v149, v123
	v_lshl_add_u64 v[72:73], v[72:73], 0, v[74:75]
	v_lshl_add_u64 v[76:77], v[76:77], 0, v[74:75]
	v_lshl_add_u64 v[80:81], v[80:81], 0, v[148:149]
	global_load_dwordx4 v[72:75], v[72:73], off
	s_nop 0
	global_load_dwordx4 v[76:79], v[76:77], off
	s_add_u32 s8, s18, s56
	global_load_dwordx2 v[160:161], v[80:81], off
	s_addc_u32 s9, s19, 0
	s_add_u32 s8, s8, s58
	s_addc_u32 s9, s9, 0
	v_lshl_add_u64 v[156:157], s[8:9], 0, v[148:149]
	s_and_b32 s8, s3, 0xffffff81
	s_lshl_b32 s46, s60, 2
	s_add_u32 s46, s50, s46
	s_addc_u32 s47, s51, 0
	v_lshl_add_u64 v[152:153], v[126:127], 0, s[56:57]
	v_lshl_add_u64 v[154:155], v[136:137], 0, s[56:57]
	s_add_u32 s56, s61, s56
	s_addc_u32 s57, s62, 0
	s_add_u32 s56, s56, s58
	s_addc_u32 s57, s57, 0
	s_add_u32 s56, s56, s52
	v_or_b32_e32 v80, s8, v131
	s_addc_u32 s57, s57, 0
	v_mov_b32_e32 v151, v123
	v_mov_b32_e32 v122, v123
	v_cmp_eq_u32_e64 s[8:9], 0, v80
	v_lshl_add_u64 v[158:159], s[56:57], 0, v[150:151]
	v_or_b32_e32 v147, s22, v129
	v_lshl_add_u64 v[162:163], v[144:145], 0, s[10:11]
	v_mov_b32_e32 v149, v188
	v_mov_b32_e32 v151, v176
	v_mov_b64_e32 v[164:165], v[122:123]
	v_mov_b64_e32 v[166:167], v[122:123]
	s_mov_b32 s56, s23
	v_mov_b32_e32 v206, 0
	v_mov_b32_e32 v207, 0
	v_mov_b32_e32 v208, 0
	v_mov_b32_e32 v209, 0
	v_mov_b32_e32 v210, 0
	v_mov_b32_e32 v211, 0
	v_mov_b32_e32 v212, 0
	v_mov_b32_e32 v213, 0
	v_and_b32_e32 v243, 15, v130
	v_lshlrev_b32_e32 v214, 4, v243
	v_add_u32_e32 v215, 0x10000, v214
	v_lshrrev_b32_e32 v244, 4, v130
	v_lshrrev_b32_e32 v245, 3, v243
	v_lshl_add_u32 v245, v244, 1, v245
	s_lshl_b32 s91, s68, 3
	v_add_u32_e32 v245, s91, v245
	v_lshlrev_b32_e32 v245, 3, v245
	v_add_u32_e32 v216, 0x1c000, v245
	s_mul_i32 s91, s68, 0x2400
	s_add_i32 s91, s91, 0x14000
	s_cmp_eq_u32 s68, 3
	s_cselect_b32 s91, 0x20800, s91
	v_mul_u32_u24_e32 v218, 0x90, v130
	v_add_u32_e32 v218, s91, v218
	v_mul_u32_u24_e32 v244, 0x90, v244
	v_lshl_add_u32 v244, v243, 3, v244
	v_add_u32_e32 v217, s91, v244
	v_lshrrev_b32_e32 v219, 2, v130
	s_cmp_lt_u32 s3, 0x80
	s_cbranch_scc1 .Lts_rw0
	v_sub_u32_e32 v219, 0, v219
.Lts_rw0:
	v_and_b32_e32 v243, 3, v130
	s_lshl_b32 s91, s68, 4
	v_lshl_add_u32 v220, v243, 2, s91
	s_lshr_b32 s91, s3, 7
	s_mul_i32 s91, s91, 0x2200000
	s_add_u32 s88, s26, s91
	s_addc_u32 s89, s27, 0
	s_add_u32 s88, s88, 0x1200000
	s_addc_u32 s89, s89, 0
	s_bfe_u32 s91, s3, 0x20005
	s_mul_i32 s91, s91, 0x880000
	s_add_u32 s88, s88, s91
	s_addc_u32 s89, s89, 0
	s_and_b32 s91, s3, 31
	s_lshl_b32 s91, s91, 6
	s_add_u32 s88, s88, s91
	s_addc_u32 s89, s89, 0
	v_and_b32_e32 v243, 7, v128
	v_lshrrev_b32_e32 v244, 3, v128
	v_lshlrev_b32_e32 v243, 5, v243
	v_lshl_add_u32 v243, v244, 8, v243
	v_add_u32_e32 v221, 0x1c000, v243

; __device__ __forceinline__ void phase_rwkv_scan(const Fr& F, int jr) {
;     ...
;                 const float inv = 1.f / fmaxf(sqrtf(ss), 1e-12f);
;                 const f32x4 av0 = *(const f32x4*)(Av + p2 * 64 + hk0), av1 = *(const f32x4*)(Av + p2 * 64 + hk0 + 4);
;                 const float av[8] = {av0.x, av0.y, av0.z, av0.w, av1.x, av1.y, av1.z, av1.w};
;                 float o1[8], o2[8], o3[8];
; #pragma unroll
;                 for (int i = 0; i < 8; ++i) { const float kkv = kq[i] * inv; o1[i] = kkv; o2[i] = kkv * av[i]; o3[i] = kr[i] * (1.f + (av[i] - 1.f) * kac[i]); }
;                 const int o = p2 * 64 + hk0;
;                 *(f32x4*)(KK + o) = (f32x4){o1[0], o1[1], o1[2], o1[3]}; *(f32x4*)(KK + o + 4) = (f32x4){o1[4], o1[5], o1[6], o1[7]};
;                 *(f32x4*)(Bv + o) = (f32x4){o2[0], o2[1], o2[2], o2[3]}; *(f32x4*)(Bv + o + 4) = (f32x4){o2[4], o2[5], o2[6], o2[7]};
;                 *(f32x4*)(KD + o) = (f32x4){o3[0], o3[1], o3[2], o3[3]}; *(f32x4*)(KD + o + 4) = (f32x4){o3[4], o3[5], o3[6], o3[7]};
;                 *(f32x4*)(Rr + o) = (f32x4){rr[0], rr[1], rr[2], rr[3]}; *(f32x4*)(Rr + o + 4) = (f32x4){rr[4], rr[5], rr[6], rr[7]};
;                 *(f32x4*)(Vv + p2 * 32 + 4 * j8) = (f32x4){lo_bf(vw.x), hi_bf(vw.x), lo_bf(vw.y), hi_bf(vw.y)};
;             }
;             if (chunk + 1 < TB / 64) {
;                 const size_t row1 = (size_t)b * TB + tokof(s, (chunk + 1) * 64 + p1), row2 = (size_t)b * TB + tokof(s, (chunk + 1) * 64 + p2);
; #pragma unroll
;                 for (int kst = 0; kst < 2; ++kst) { Aw[kst] = *(const bf16x8*)(LM + row1 * 256 + 64 * s + 32 * kst + 8 * lq); Aa[kst] = *(const bf16x8*)(LM + row1 * 256 + 128 + 64 * s + 32 * kst + 8 * lq); }
;                 kw = *(const u32x4*)(Kb + row2 * D + h * 64 + hk0); rw = *(const u32x4*)(Rb + row2 * D + h * 64 + hk0); vw = *(const u32x2*)(Vb + row2 * D + h * 64 + 32 * half + 4 * j8);
;             }
;             LDS_BAR();
;             {
;                 float* Ypw = Yp + wave * 1024;
;                 unsigned a1 = (unsigned)(size_t)(__attribute__((address_space(3))) float*)(Wv + ks), a2 = (unsigned)(size_t)(__attribute__((address_space(3))) float*)(Rr + ks),
;                          a3 = (unsigned)(size_t)(__attribute__((address_space(3))) float*)(Vv + rloc), a4 = (unsigned)(size_t)(__attribute__((address_space(3))) float*)(Ypw + lane);
.LBB0_558:
	s_or_b64 exec, exec, s[10:11]
	v_add_f32_e32 v104, v104, v105
	v_mul_f32_e32 v105, 0x4f800000, v104
	v_cmp_gt_f32_e32 vcc, s53, v104
	s_nop 1
	v_cndmask_b32_e32 v104, v104, v105, vcc
	v_sqrt_f32_e32 v105, v104
	s_nop 0
	v_add_u32_e32 v106, -1, v105
	v_fma_f32 v108, -v106, v105, v104
	v_add_u32_e32 v107, 1, v105
	v_cmp_ge_f32_e64 s[10:11], 0, v108
	s_nop 1
	v_cndmask_b32_e64 v106, v105, v106, s[10:11]
	v_fma_f32 v105, -v107, v105, v104
	v_cmp_lt_f32_e64 s[10:11], 0, v105
	s_nop 1
	v_cndmask_b32_e64 v105, v106, v107, s[10:11]
	v_mul_f32_e32 v106, 0x37800000, v105
	v_cndmask_b32_e32 v105, v105, v106, vcc
	v_cmp_class_f32_e32 vcc, v104, v189
	s_nop 1
	v_cndmask_b32_e32 v104, v105, v104, vcc
	v_max_f32_e32 v104, 0x2b8cbccc, v104
	v_div_scale_f32 v105, s[10:11], v104, v104, 1.0
	v_rcp_f32_e32 v106, v105
	s_add_i32 s10, s56, 1
	s_cmpk_eq_i32 s56, 0x43
	v_fma_f32 v107, -v105, v106, 1.0
	v_fmac_f32_e32 v106, v107, v106
	v_div_scale_f32 v107, vcc, 1.0, v104, 1.0
	v_mul_f32_e32 v108, v107, v106
	v_fma_f32 v109, -v105, v108, v107
	v_fmac_f32_e32 v108, v109, v106
	v_fma_f32 v105, -v105, v108, v107
	v_div_fmas_f32 v105, v105, v106, v108
	v_div_fixup_f32 v112, v105, v104, 1.0
	ds_read_b128 v[104:107], v169
	ds_read_b128 v[108:111], v169 offset:16
	v_pk_mul_f32 v[96:97], v[96:97], v[112:113] op_sel_hi:[1,0]
	v_pk_mul_f32 v[98:99], v[98:99], v[112:113] op_sel_hi:[1,0]
	v_pk_mul_f32 v[100:101], v[100:101], v[112:113] op_sel_hi:[1,0]
	v_pk_mul_f32 v[102:103], v[102:103], v[112:113] op_sel_hi:[1,0]
	ds_write_b128 v170, v[96:99] offset:16384
	ds_write_b128 v170, v[100:103] offset:16400
	s_waitcnt lgkmcnt(3)
	v_pk_mul_f32 v[98:99], v[98:99], v[106:107]
	v_pk_mul_f32 v[96:97], v[96:97], v[104:105]
	ds_write_b128 v170, v[96:99] offset:32768
	s_waitcnt lgkmcnt(3)
	v_pk_mul_f32 v[98:99], v[102:103], v[110:111]
	v_pk_mul_f32 v[96:97], v[100:101], v[108:109]
	ds_write_b128 v170, v[96:99] offset:32784
	v_pk_add_f32 v[96:97], v[106:107], -1.0 op_sel_hi:[1,0]
	v_pk_add_f32 v[98:99], v[104:105], -1.0 op_sel_hi:[1,0]
	v_pk_fma_f32 v[96:97], v[54:55], v[96:97], 1.0 op_sel_hi:[1,1,0]
	v_pk_fma_f32 v[100:101], v[52:53], v[98:99], 1.0 op_sel_hi:[1,1,0]
	v_pk_mul_f32 v[98:99], v[96:97], v[92:93]
	v_pk_mul_f32 v[96:97], v[100:101], v[88:89]
	v_pk_add_f32 v[88:89], v[110:111], -1.0 op_sel_hi:[1,0]
	v_pk_add_f32 v[92:93], v[108:109], -1.0 op_sel_hi:[1,0]
	ds_write_b128 v170, v[96:99] offset:49152
	v_pk_fma_f32 v[88:89], v[50:51], v[88:89], 1.0 op_sel_hi:[1,1,0]
	v_pk_fma_f32 v[96:97], v[48:49], v[92:93], 1.0 op_sel_hi:[1,1,0]
	v_pk_mul_f32 v[92:93], v[88:89], v[94:95]
	v_pk_mul_f32 v[90:91], v[96:97], v[90:91]
	ds_write_b128 v170, v[90:93] offset:49168
	ds_write_b128 v171, v[84:87]
	ds_write_b128 v171, v[80:83] offset:16
	v_lshlrev_b32_e32 v80, 16, v160
	v_and_b32_e32 v81, 0xffff0000, v160
	v_mov_b32_e32 v82, v81
	v_mov_b32_e32 v83, v80
	ds_write_b128 v221, v[80:83]
	v_lshlrev_b32_e32 v84, 16, v161
	v_and_b32_e32 v85, 0xffff0000, v161
	v_mov_b32_e32 v86, v85
	v_mov_b32_e32 v87, v84
	ds_write_b128 v221, v[84:87] offset:16
	s_cbranch_scc1 .LBB0_560
	s_lshl_b32 s11, s10, 6
	s_cmp_gt_u32 s56, 2
	v_or_b32_e32 v56, s11, v121
	s_cselect_b32 s56, s54, 0xff
	v_add_u32_e32 v58, s11, v129
	v_sub_u32_e32 v57, s56, v56
	v_cmp_lt_u32_e32 vcc, s37, v58
	v_cndmask_b32_e64 v56, v57, v56, s[6:7]
	v_ashrrev_i32_e32 v57, 31, v56
	v_cndmask_b32_e32 v59, v133, v192, vcc
	v_sub_u32_e32 v59, v59, v58
	v_lshl_add_u64 v[56:57], v[56:57], 0, s[22:23]
	v_cndmask_b32_e64 v72, v59, v58, s[6:7]
	v_ashrrev_i32_e32 v73, 31, v72
	v_lshlrev_b64 v[56:57], 9, v[56:57]
	v_lshl_add_u64 v[68:69], v[162:163], 0, v[56:57]
	v_lshl_add_u64 v[72:73], v[72:73], 0, s[22:23]
	global_load_dwordx4 v[56:59], v[68:69], off
	global_load_dwordx4 v[60:63], v[68:69], off offset:64
	global_load_dwordx4 v[64:67], v[68:69], off offset:256
	s_nop 0
	global_load_dwordx4 v[68:71], v[68:69], off offset:320
	v_lshlrev_b64 v[80:81], 11, v[72:73]
	v_lshl_add_u64 v[72:73], v[152:153], 0, v[80:81]
	v_lshl_add_u64 v[76:77], v[154:155], 0, v[80:81]
	v_lshl_add_u64 v[80:81], v[156:157], 0, v[80:81]
	global_load_dwordx4 v[72:75], v[72:73], off
	s_nop 0
	global_load_dwordx4 v[76:79], v[76:77], off
	s_nop 0
	global_load_dwordx2 v[160:161], v[80:81], off
.LBB0_560:
	s_waitcnt lgkmcnt(0)
	s_barrier
	s_cmp_gt_u32 s68, 3
	s_cbranch_scc1 .Lrw0_skip
	s_mov_b32 s87, 0
	v_mov_b32_e32 v240, v214
	v_mov_b32_e32 v241, v215
	v_mov_b32_e32 v242, v216
	ds_read_b128 v[84:87], v214 offset:16384
	ds_read_b64 v[100:101], v216
	ds_read_b128 v[92:95], v214 offset:49152
	ds_read_b128 v[80:83], v214
	ds_read_b128 v[88:91], v214 offset:32768
	ds_read_b128 v[96:99], v215
	s_add_i32 s91, s10, -1
	s_lshl_b32 s92, s91, 6
	s_cmp_lt_u32 s91, 4
	s_movk_i32 s93, 0x11ff
	s_cselect_b32 s93, 0xff, s93
	s_sub_i32 s93, s93, s92
	s_cmp_lt_u32 s3, 0x80
	s_cselect_b32 s90, s92, s93
	s_cselect_b32 s94, 16, -16
	s_waitcnt lgkmcnt(0)
; template <int CTRL> __device__ __forceinline__ float dppf(float x) { return __builtin_bit_cast(float, __builtin_amdgcn_update_dpp(0, __builtin_bit_cast(int, x), CTRL, 0xF, 0xF, false)); }
; __device__ __forceinline__ void phase_rwkv_scan(const Fr& F, int jr) {
;     ...
;                 for (int pg = 0; pg < 64; pg += 16) {
; #pragma unroll
;                     for (int pi = 0; pi < 16; ++pi) {
;                         const int p = pg + pi, pn = p < 63 ? p + 1 : 63;
;                         const f32x4 w4n = PW[pn * 16], k4n = PW[1024 + pn * 16], b4n = PW[2048 + pn * 16], d4n = PW[3072 + pn * 16], r4n = PR[pn * 16];
;                         const float vvn = PV[pn * 32];
;                         f32x2 t = S01 * k4.xy; t = S23 * k4.zw + t; float sa = t.x + t.y;
;                         sa += dppf<0x128>(sa);
;                         const f32x2 dv01 = d4.xy * vv, dv23 = d4.zw * vv;
;                         sa += dppf<0x124>(sa);
;                         const f32x2 e01 = S01 * w4.xy + dv01;
;                         sa += dppf<0x122>(sa);
;                         const f32x2 e23 = S23 * w4.zw + dv23;
;                         sa += dppf<0x121>(sa);
;                         S01 = e01 - b4.xy * sa; S23 = e23 - b4.zw * sa;
;                         f32x2 u = S01 * r4.xy; u = S23 * r4.zw + u;
;                         PY[pi * 64] = u.x + u.y;
;                         w4 = w4n; k4 = k4n; b4 = b4n; d4 = d4n; r4 = r4n; vv = vvn;
;                     }
.Lrw0_group:
	ds_read_b128 v[106:109], v240 offset:16640
	ds_read_b64 v[118:119], v242 offset:256
	ds_read_b128 v[114:117], v240 offset:49408
	v_pk_mul_f32 v[226:227], v[206:207], v[84:85] op_sel_hi:[1,0]
	v_pk_mul_f32 v[232:233], v[100:101], v[92:93] op_sel_hi:[1,0]
	v_pk_fma_f32 v[226:227], v[208:209], v[84:85], v[226:227] op_sel:[0,1,0]
	v_pk_mul_f32 v[234:235], v[100:101], v[92:93] op_sel:[0,1]
	v_pk_fma_f32 v[226:227], v[210:211], v[86:87], v[226:227] op_sel_hi:[1,0,1]
	v_pk_mul_f32 v[236:237], v[100:101], v[94:95] op_sel_hi:[1,0]
	v_pk_fma_f32 v[226:227], v[212:213], v[86:87], v[226:227] op_sel:[0,1,0]
	v_pk_mul_f32 v[238:239], v[100:101], v[94:95] op_sel:[0,1]
	s_nop 0
	v_add_f32_dpp v230, v227, v226 row_ror:8 row_mask:0xf bank_mask:0xf
	ds_read_b128 v[102:105], v240 offset:256
	v_pk_fma_f32 v[232:233], v[206:207], v[80:81], v[232:233] op_sel_hi:[1,0,1]
	v_add_f32_dpp v230, v230, v230 quad_perm:[1,0,3,2] row_mask:0xf bank_mask:0xf
	v_pk_fma_f32 v[234:235], v[208:209], v[80:81], v[234:235] op_sel:[0,1,0]
	v_pk_fma_f32 v[236:237], v[210:211], v[82:83], v[236:237] op_sel_hi:[1,0,1]
	v_add_f32_dpp v230, v230, v230 quad_perm:[2,3,0,1] row_mask:0xf bank_mask:0xf
	v_pk_fma_f32 v[238:239], v[212:213], v[82:83], v[238:239] op_sel:[0,1,0]
	s_nop 0
	v_add_f32_dpp v230, v230, v230 row_half_mirror row_mask:0xf bank_mask:0xf
	s_nop 0
	s_nop 0
	v_mov_b32_dpp v231, v230 row_ror:8 row_mask:0xf bank_mask:0xf
	ds_read_b128 v[110:113], v240 offset:33024
	ds_read_b128 v[222:225], v241 offset:256
	v_pk_fma_f32 v[206:207], v[88:89], v[230:231], v[232:233] op_sel_hi:[0,1,1] neg_lo:[1,0,0] neg_hi:[1,0,0]
	v_pk_fma_f32 v[208:209], v[88:89], v[230:231], v[234:235] op_sel:[1,0,0] neg_lo:[1,0,0] neg_hi:[1,0,0]
	v_pk_fma_f32 v[210:211], v[90:91], v[230:231], v[236:237] op_sel_hi:[0,1,1] neg_lo:[1,0,0] neg_hi:[1,0,0]
	v_pk_fma_f32 v[212:213], v[90:91], v[230:231], v[238:239] op_sel:[1,0,0] neg_lo:[1,0,0] neg_hi:[1,0,0]
	ds_read_b128 v[84:87], v240 offset:16896
	ds_read_b64 v[100:101], v242 offset:512
	ds_read_b128 v[92:95], v240 offset:49664
	s_waitcnt lgkmcnt(6)
	v_pk_mul_f32 v[226:227], v[206:207], v[106:107] op_sel_hi:[1,0]
	v_pk_mul_f32 v[228:229], v[206:207], v[96:97] op_sel_hi:[1,0]
	v_pk_fma_f32 v[226:227], v[208:209], v[106:107], v[226:227] op_sel:[0,1,0]
	v_pk_fma_f32 v[228:229], v[208:209], v[96:97], v[228:229] op_sel:[0,1,0]
	v_pk_fma_f32 v[226:227], v[210:211], v[108:109], v[226:227] op_sel_hi:[1,0,1]
	v_pk_fma_f32 v[228:229], v[210:211], v[98:99], v[228:229] op_sel_hi:[1,0,1]
	v_pk_fma_f32 v[226:227], v[212:213], v[108:109], v[226:227] op_sel:[0,1,0]
	v_pk_fma_f32 v[228:229], v[212:213], v[98:99], v[228:229] op_sel:[0,1,0]
	v_pk_mul_f32 v[232:233], v[118:119], v[114:115] op_sel_hi:[1,0]
	ds_write_b64 v217, v[228:229] offset:0
	v_add_f32_dpp v230, v227, v226 row_ror:8 row_mask:0xf bank_mask:0xf
	v_pk_mul_f32 v[234:235], v[118:119], v[114:115] op_sel:[0,1]
	v_pk_mul_f32 v[236:237], v[118:119], v[116:117] op_sel_hi:[1,0]
	v_add_f32_dpp v230, v230, v230 quad_perm:[1,0,3,2] row_mask:0xf bank_mask:0xf
	v_pk_mul_f32 v[238:239], v[118:119], v[116:117] op_sel:[0,1]
	ds_read_b128 v[80:83], v240 offset:512
	v_add_f32_dpp v230, v230, v230 quad_perm:[2,3,0,1] row_mask:0xf bank_mask:0xf
	s_waitcnt lgkmcnt(7)
	v_pk_fma_f32 v[232:233], v[206:207], v[102:103], v[232:233] op_sel_hi:[1,0,1]
	v_pk_fma_f32 v[234:235], v[208:209], v[102:103], v[234:235] op_sel:[0,1,0]
	v_add_f32_dpp v230, v230, v230 row_half_mirror row_mask:0xf bank_mask:0xf
	v_pk_fma_f32 v[236:237], v[210:211], v[104:105], v[236:237] op_sel_hi:[1,0,1]
	v_pk_fma_f32 v[238:239], v[212:213], v[104:105], v[238:239] op_sel:[0,1,0]
	v_mov_b32_dpp v231, v230 row_ror:8 row_mask:0xf bank_mask:0xf
	ds_read_b128 v[88:91], v240 offset:33280
	ds_read_b128 v[96:99], v241 offset:512
	s_waitcnt lgkmcnt(8)
	v_pk_fma_f32 v[206:207], v[110:111], v[230:231], v[232:233] op_sel_hi:[0,1,1] neg_lo:[1,0,0] neg_hi:[1,0,0]
	v_pk_fma_f32 v[208:209], v[110:111], v[230:231], v[234:235] op_sel:[1,0,0] neg_lo:[1,0,0] neg_hi:[1,0,0]
	v_pk_fma_f32 v[210:211], v[112:113], v[230:231], v[236:237] op_sel_hi:[0,1,1] neg_lo:[1,0,0] neg_hi:[1,0,0]
	v_pk_fma_f32 v[212:213], v[112:113], v[230:231], v[238:239] op_sel:[1,0,0] neg_lo:[1,0,0] neg_hi:[1,0,0]
	ds_read_b128 v[106:109], v240 offset:17152
	ds_read_b64 v[118:119], v242 offset:768
	ds_read_b128 v[114:117], v240 offset:49920
	s_waitcnt lgkmcnt(7)
	v_pk_mul_f32 v[226:227], v[206:207], v[84:85] op_sel_hi:[1,0]
	v_pk_mul_f32 v[228:229], v[206:207], v[222:223] op_sel_hi:[1,0]
	v_pk_fma_f32 v[226:227], v[208:209], v[84:85], v[226:227] op_sel:[0,1,0]
	v_pk_fma_f32 v[228:229], v[208:209], v[222:223], v[228:229] op_sel:[0,1,0]
	v_pk_fma_f32 v[226:227], v[210:211], v[86:87], v[226:227] op_sel_hi:[1,0,1]
	v_pk_fma_f32 v[228:229], v[210:211], v[224:225], v[228:229] op_sel_hi:[1,0,1]
	v_pk_fma_f32 v[226:227], v[212:213], v[86:87], v[226:227] op_sel:[0,1,0]
	v_pk_fma_f32 v[228:229], v[212:213], v[224:225], v[228:229] op_sel:[0,1,0]
	v_pk_mul_f32 v[232:233], v[100:101], v[92:93] op_sel_hi:[1,0]
	ds_write_b64 v217, v[228:229] offset:576
	v_add_f32_dpp v230, v227, v226 row_ror:8 row_mask:0xf bank_mask:0xf
	v_pk_mul_f32 v[234:235], v[100:101], v[92:93] op_sel:[0,1]
	v_pk_mul_f32 v[236:237], v[100:101], v[94:95] op_sel_hi:[1,0]
	v_add_f32_dpp v230, v230, v230 quad_perm:[1,0,3,2] row_mask:0xf bank_mask:0xf
	v_pk_mul_f32 v[238:239], v[100:101], v[94:95] op_sel:[0,1]
	ds_read_b128 v[102:105], v240 offset:768
	v_add_f32_dpp v230, v230, v230 quad_perm:[2,3,0,1] row_mask:0xf bank_mask:0xf
	s_waitcnt lgkmcnt(7)
; template <int CTRL> __device__ __forceinline__ float dppf(float x) { return __builtin_bit_cast(float, __builtin_amdgcn_update_dpp(0, __builtin_bit_cast(int, x), CTRL, 0xF, 0xF, false)); }
; __device__ __forceinline__ void phase_rwkv_scan(const Fr& F, int jr) {
;     ...
;                 for (int pg = 0; pg < 64; pg += 16) {
; #pragma unroll
;                     for (int pi = 0; pi < 16; ++pi) {
;                         const int p = pg + pi, pn = p < 63 ? p + 1 : 63;
;                         const f32x4 w4n = PW[pn * 16], k4n = PW[1024 + pn * 16], b4n = PW[2048 + pn * 16], d4n = PW[3072 + pn * 16], r4n = PR[pn * 16];
;                         const float vvn = PV[pn * 32];
;                         f32x2 t = S01 * k4.xy; t = S23 * k4.zw + t; float sa = t.x + t.y;
;                         sa += dppf<0x128>(sa);
;                         const f32x2 dv01 = d4.xy * vv, dv23 = d4.zw * vv;
;                         sa += dppf<0x124>(sa);
;                         const f32x2 e01 = S01 * w4.xy + dv01;
;                         sa += dppf<0x122>(sa);
;                         const f32x2 e23 = S23 * w4.zw + dv23;
;                         sa += dppf<0x121>(sa);
;                         S01 = e01 - b4.xy * sa; S23 = e23 - b4.zw * sa;
;                         f32x2 u = S01 * r4.xy; u = S23 * r4.zw + u;
;                         PY[pi * 64] = u.x + u.y;
;                         w4 = w4n; k4 = k4n; b4 = b4n; d4 = d4n; r4 = r4n; vv = vvn;
;                     }
	v_pk_fma_f32 v[232:233], v[206:207], v[80:81], v[232:233] op_sel_hi:[1,0,1]
	v_pk_fma_f32 v[234:235], v[208:209], v[80:81], v[234:235] op_sel:[0,1,0]
	v_add_f32_dpp v230, v230, v230 row_half_mirror row_mask:0xf bank_mask:0xf
	v_pk_fma_f32 v[236:237], v[210:211], v[82:83], v[236:237] op_sel_hi:[1,0,1]
	v_pk_fma_f32 v[238:239], v[212:213], v[82:83], v[238:239] op_sel:[0,1,0]
	v_mov_b32_dpp v231, v230 row_ror:8 row_mask:0xf bank_mask:0xf
	ds_read_b128 v[110:113], v240 offset:33536
	ds_read_b128 v[222:225], v241 offset:768
	s_waitcnt lgkmcnt(8)
	v_pk_fma_f32 v[206:207], v[88:89], v[230:231], v[232:233] op_sel_hi:[0,1,1] neg_lo:[1,0,0] neg_hi:[1,0,0]
	v_pk_fma_f32 v[208:209], v[88:89], v[230:231], v[234:235] op_sel:[1,0,0] neg_lo:[1,0,0] neg_hi:[1,0,0]
	v_pk_fma_f32 v[210:211], v[90:91], v[230:231], v[236:237] op_sel_hi:[0,1,1] neg_lo:[1,0,0] neg_hi:[1,0,0]
	v_pk_fma_f32 v[212:213], v[90:91], v[230:231], v[238:239] op_sel:[1,0,0] neg_lo:[1,0,0] neg_hi:[1,0,0]
	ds_read_b128 v[84:87], v240 offset:17408
	ds_read_b64 v[100:101], v242 offset:1024
	ds_read_b128 v[92:95], v240 offset:50176
	s_waitcnt lgkmcnt(7)
	v_pk_mul_f32 v[226:227], v[206:207], v[106:107] op_sel_hi:[1,0]
	v_pk_mul_f32 v[228:229], v[206:207], v[96:97] op_sel_hi:[1,0]
	v_pk_fma_f32 v[226:227], v[208:209], v[106:107], v[226:227] op_sel:[0,1,0]
	v_pk_fma_f32 v[228:229], v[208:209], v[96:97], v[228:229] op_sel:[0,1,0]
	v_pk_fma_f32 v[226:227], v[210:211], v[108:109], v[226:227] op_sel_hi:[1,0,1]
	v_pk_fma_f32 v[228:229], v[210:211], v[98:99], v[228:229] op_sel_hi:[1,0,1]
	v_pk_fma_f32 v[226:227], v[212:213], v[108:109], v[226:227] op_sel:[0,1,0]
	v_pk_fma_f32 v[228:229], v[212:213], v[98:99], v[228:229] op_sel:[0,1,0]
	v_pk_mul_f32 v[232:233], v[118:119], v[114:115] op_sel_hi:[1,0]
	ds_write_b64 v217, v[228:229] offset:1152
	v_add_f32_dpp v230, v227, v226 row_ror:8 row_mask:0xf bank_mask:0xf
	v_pk_mul_f32 v[234:235], v[118:119], v[114:115] op_sel:[0,1]
	v_pk_mul_f32 v[236:237], v[118:119], v[116:117] op_sel_hi:[1,0]
	v_add_f32_dpp v230, v230, v230 quad_perm:[1,0,3,2] row_mask:0xf bank_mask:0xf
	v_pk_mul_f32 v[238:239], v[118:119], v[116:117] op_sel:[0,1]
	ds_read_b128 v[80:83], v240 offset:1024
	v_add_f32_dpp v230, v230, v230 quad_perm:[2,3,0,1] row_mask:0xf bank_mask:0xf
	s_waitcnt lgkmcnt(7)
	v_pk_fma_f32 v[232:233], v[206:207], v[102:103], v[232:233] op_sel_hi:[1,0,1]
	v_pk_fma_f32 v[234:235], v[208:209], v[102:103], v[234:235] op_sel:[0,1,0]
	v_add_f32_dpp v230, v230, v230 row_half_mirror row_mask:0xf bank_mask:0xf
	v_pk_fma_f32 v[236:237], v[210:211], v[104:105], v[236:237] op_sel_hi:[1,0,1]
	v_pk_fma_f32 v[238:239], v[212:213], v[104:105], v[238:239] op_sel:[0,1,0]
	v_mov_b32_dpp v231, v230 row_ror:8 row_mask:0xf bank_mask:0xf
	ds_read_b128 v[88:91], v240 offset:33792
	ds_read_b128 v[96:99], v241 offset:1024
	s_waitcnt lgkmcnt(8)
	v_pk_fma_f32 v[206:207], v[110:111], v[230:231], v[232:233] op_sel_hi:[0,1,1] neg_lo:[1,0,0] neg_hi:[1,0,0]
	v_pk_fma_f32 v[208:209], v[110:111], v[230:231], v[234:235] op_sel:[1,0,0] neg_lo:[1,0,0] neg_hi:[1,0,0]
	v_pk_fma_f32 v[210:211], v[112:113], v[230:231], v[236:237] op_sel_hi:[0,1,1] neg_lo:[1,0,0] neg_hi:[1,0,0]
	v_pk_fma_f32 v[212:213], v[112:113], v[230:231], v[238:239] op_sel:[1,0,0] neg_lo:[1,0,0] neg_hi:[1,0,0]
	ds_read_b128 v[106:109], v240 offset:17664
	ds_read_b64 v[118:119], v242 offset:1280
	ds_read_b128 v[114:117], v240 offset:50432
	s_waitcnt lgkmcnt(7)
	v_pk_mul_f32 v[226:227], v[206:207], v[84:85] op_sel_hi:[1,0]
	v_pk_mul_f32 v[228:229], v[206:207], v[222:223] op_sel_hi:[1,0]
	v_pk_fma_f32 v[226:227], v[208:209], v[84:85], v[226:227] op_sel:[0,1,0]
	v_pk_fma_f32 v[228:229], v[208:209], v[222:223], v[228:229] op_sel:[0,1,0]
	v_pk_fma_f32 v[226:227], v[210:211], v[86:87], v[226:227] op_sel_hi:[1,0,1]
	v_pk_fma_f32 v[228:229], v[210:211], v[224:225], v[228:229] op_sel_hi:[1,0,1]
	v_pk_fma_f32 v[226:227], v[212:213], v[86:87], v[226:227] op_sel:[0,1,0]
	v_pk_fma_f32 v[228:229], v[212:213], v[224:225], v[228:229] op_sel:[0,1,0]
	v_pk_mul_f32 v[232:233], v[100:101], v[92:93] op_sel_hi:[1,0]
	ds_write_b64 v217, v[228:229] offset:1728
	v_add_f32_dpp v230, v227, v226 row_ror:8 row_mask:0xf bank_mask:0xf
	v_pk_mul_f32 v[234:235], v[100:101], v[92:93] op_sel:[0,1]
	v_pk_mul_f32 v[236:237], v[100:101], v[94:95] op_sel_hi:[1,0]
	v_add_f32_dpp v230, v230, v230 quad_perm:[1,0,3,2] row_mask:0xf bank_mask:0xf
	v_pk_mul_f32 v[238:239], v[100:101], v[94:95] op_sel:[0,1]
	ds_read_b128 v[102:105], v240 offset:1280
	v_add_f32_dpp v230, v230, v230 quad_perm:[2,3,0,1] row_mask:0xf bank_mask:0xf
	s_waitcnt lgkmcnt(7)
	v_pk_fma_f32 v[232:233], v[206:207], v[80:81], v[232:233] op_sel_hi:[1,0,1]
	v_pk_fma_f32 v[234:235], v[208:209], v[80:81], v[234:235] op_sel:[0,1,0]
	v_add_f32_dpp v230, v230, v230 row_half_mirror row_mask:0xf bank_mask:0xf
	v_pk_fma_f32 v[236:237], v[210:211], v[82:83], v[236:237] op_sel_hi:[1,0,1]
	v_pk_fma_f32 v[238:239], v[212:213], v[82:83], v[238:239] op_sel:[0,1,0]
	v_mov_b32_dpp v231, v230 row_ror:8 row_mask:0xf bank_mask:0xf
	ds_read_b128 v[110:113], v240 offset:34048
	ds_read_b128 v[222:225], v241 offset:1280
	s_waitcnt lgkmcnt(8)
	v_pk_fma_f32 v[206:207], v[88:89], v[230:231], v[232:233] op_sel_hi:[0,1,1] neg_lo:[1,0,0] neg_hi:[1,0,0]
	v_pk_fma_f32 v[208:209], v[88:89], v[230:231], v[234:235] op_sel:[1,0,0] neg_lo:[1,0,0] neg_hi:[1,0,0]
	v_pk_fma_f32 v[210:211], v[90:91], v[230:231], v[236:237] op_sel_hi:[0,1,1] neg_lo:[1,0,0] neg_hi:[1,0,0]
	v_pk_fma_f32 v[212:213], v[90:91], v[230:231], v[238:239] op_sel:[1,0,0] neg_lo:[1,0,0] neg_hi:[1,0,0]
	ds_read_b128 v[84:87], v240 offset:17920
	ds_read_b64 v[100:101], v242 offset:1536
	ds_read_b128 v[92:95], v240 offset:50688
	s_waitcnt lgkmcnt(7)
; template <int CTRL> __device__ __forceinline__ float dppf(float x) { return __builtin_bit_cast(float, __builtin_amdgcn_update_dpp(0, __builtin_bit_cast(int, x), CTRL, 0xF, 0xF, false)); }
; __device__ __forceinline__ void phase_rwkv_scan(const Fr& F, int jr) {
;     ...
;                 for (int pg = 0; pg < 64; pg += 16) {
; #pragma unroll
;                     for (int pi = 0; pi < 16; ++pi) {
;                         const int p = pg + pi, pn = p < 63 ? p + 1 : 63;
;                         const f32x4 w4n = PW[pn * 16], k4n = PW[1024 + pn * 16], b4n = PW[2048 + pn * 16], d4n = PW[3072 + pn * 16], r4n = PR[pn * 16];
;                         const float vvn = PV[pn * 32];
;                         f32x2 t = S01 * k4.xy; t = S23 * k4.zw + t; float sa = t.x + t.y;
;                         sa += dppf<0x128>(sa);
;                         const f32x2 dv01 = d4.xy * vv, dv23 = d4.zw * vv;
;                         sa += dppf<0x124>(sa);
;                         const f32x2 e01 = S01 * w4.xy + dv01;
;                         sa += dppf<0x122>(sa);
;                         const f32x2 e23 = S23 * w4.zw + dv23;
;                         sa += dppf<0x121>(sa);
;                         S01 = e01 - b4.xy * sa; S23 = e23 - b4.zw * sa;
;                         f32x2 u = S01 * r4.xy; u = S23 * r4.zw + u;
;                         PY[pi * 64] = u.x + u.y;
;                         w4 = w4n; k4 = k4n; b4 = b4n; d4 = d4n; r4 = r4n; vv = vvn;
;                     }
	v_pk_mul_f32 v[226:227], v[206:207], v[106:107] op_sel_hi:[1,0]
	v_pk_mul_f32 v[228:229], v[206:207], v[96:97] op_sel_hi:[1,0]
	v_pk_fma_f32 v[226:227], v[208:209], v[106:107], v[226:227] op_sel:[0,1,0]
	v_pk_fma_f32 v[228:229], v[208:209], v[96:97], v[228:229] op_sel:[0,1,0]
	v_pk_fma_f32 v[226:227], v[210:211], v[108:109], v[226:227] op_sel_hi:[1,0,1]
	v_pk_fma_f32 v[228:229], v[210:211], v[98:99], v[228:229] op_sel_hi:[1,0,1]
	v_pk_fma_f32 v[226:227], v[212:213], v[108:109], v[226:227] op_sel:[0,1,0]
	v_pk_fma_f32 v[228:229], v[212:213], v[98:99], v[228:229] op_sel:[0,1,0]
	v_pk_mul_f32 v[232:233], v[118:119], v[114:115] op_sel_hi:[1,0]
	ds_write_b64 v217, v[228:229] offset:2304
	v_add_f32_dpp v230, v227, v226 row_ror:8 row_mask:0xf bank_mask:0xf
	v_pk_mul_f32 v[234:235], v[118:119], v[114:115] op_sel:[0,1]
	v_pk_mul_f32 v[236:237], v[118:119], v[116:117] op_sel_hi:[1,0]
	v_add_f32_dpp v230, v230, v230 quad_perm:[1,0,3,2] row_mask:0xf bank_mask:0xf
	v_pk_mul_f32 v[238:239], v[118:119], v[116:117] op_sel:[0,1]
	ds_read_b128 v[80:83], v240 offset:1536
	v_add_f32_dpp v230, v230, v230 quad_perm:[2,3,0,1] row_mask:0xf bank_mask:0xf
	s_waitcnt lgkmcnt(7)
	v_pk_fma_f32 v[232:233], v[206:207], v[102:103], v[232:233] op_sel_hi:[1,0,1]
	v_pk_fma_f32 v[234:235], v[208:209], v[102:103], v[234:235] op_sel:[0,1,0]
	v_add_f32_dpp v230, v230, v230 row_half_mirror row_mask:0xf bank_mask:0xf
	v_pk_fma_f32 v[236:237], v[210:211], v[104:105], v[236:237] op_sel_hi:[1,0,1]
	v_pk_fma_f32 v[238:239], v[212:213], v[104:105], v[238:239] op_sel:[0,1,0]
	v_mov_b32_dpp v231, v230 row_ror:8 row_mask:0xf bank_mask:0xf
	ds_read_b128 v[88:91], v240 offset:34304
	ds_read_b128 v[96:99], v241 offset:1536
	s_waitcnt lgkmcnt(8)
	v_pk_fma_f32 v[206:207], v[110:111], v[230:231], v[232:233] op_sel_hi:[0,1,1] neg_lo:[1,0,0] neg_hi:[1,0,0]
	v_pk_fma_f32 v[208:209], v[110:111], v[230:231], v[234:235] op_sel:[1,0,0] neg_lo:[1,0,0] neg_hi:[1,0,0]
	v_pk_fma_f32 v[210:211], v[112:113], v[230:231], v[236:237] op_sel_hi:[0,1,1] neg_lo:[1,0,0] neg_hi:[1,0,0]
	v_pk_fma_f32 v[212:213], v[112:113], v[230:231], v[238:239] op_sel:[1,0,0] neg_lo:[1,0,0] neg_hi:[1,0,0]
	ds_read_b128 v[106:109], v240 offset:18176
	ds_read_b64 v[118:119], v242 offset:1792
	ds_read_b128 v[114:117], v240 offset:50944
	s_waitcnt lgkmcnt(7)
	v_pk_mul_f32 v[226:227], v[206:207], v[84:85] op_sel_hi:[1,0]
	v_pk_mul_f32 v[228:229], v[206:207], v[222:223] op_sel_hi:[1,0]
	v_pk_fma_f32 v[226:227], v[208:209], v[84:85], v[226:227] op_sel:[0,1,0]
	v_pk_fma_f32 v[228:229], v[208:209], v[222:223], v[228:229] op_sel:[0,1,0]
	v_pk_fma_f32 v[226:227], v[210:211], v[86:87], v[226:227] op_sel_hi:[1,0,1]
	v_pk_fma_f32 v[228:229], v[210:211], v[224:225], v[228:229] op_sel_hi:[1,0,1]
	v_pk_fma_f32 v[226:227], v[212:213], v[86:87], v[226:227] op_sel:[0,1,0]
	v_pk_fma_f32 v[228:229], v[212:213], v[224:225], v[228:229] op_sel:[0,1,0]
	v_pk_mul_f32 v[232:233], v[100:101], v[92:93] op_sel_hi:[1,0]
	ds_write_b64 v217, v[228:229] offset:2880
	v_add_f32_dpp v230, v227, v226 row_ror:8 row_mask:0xf bank_mask:0xf
	v_pk_mul_f32 v[234:235], v[100:101], v[92:93] op_sel:[0,1]
	v_pk_mul_f32 v[236:237], v[100:101], v[94:95] op_sel_hi:[1,0]
	v_add_f32_dpp v230, v230, v230 quad_perm:[1,0,3,2] row_mask:0xf bank_mask:0xf
	v_pk_mul_f32 v[238:239], v[100:101], v[94:95] op_sel:[0,1]
	ds_read_b128 v[102:105], v240 offset:1792
	v_add_f32_dpp v230, v230, v230 quad_perm:[2,3,0,1] row_mask:0xf bank_mask:0xf
	s_waitcnt lgkmcnt(7)
	v_pk_fma_f32 v[232:233], v[206:207], v[80:81], v[232:233] op_sel_hi:[1,0,1]
	v_pk_fma_f32 v[234:235], v[208:209], v[80:81], v[234:235] op_sel:[0,1,0]
	v_add_f32_dpp v230, v230, v230 row_half_mirror row_mask:0xf bank_mask:0xf
	v_pk_fma_f32 v[236:237], v[210:211], v[82:83], v[236:237] op_sel_hi:[1,0,1]
	v_pk_fma_f32 v[238:239], v[212:213], v[82:83], v[238:239] op_sel:[0,1,0]
	v_mov_b32_dpp v231, v230 row_ror:8 row_mask:0xf bank_mask:0xf
	ds_read_b128 v[110:113], v240 offset:34560
	ds_read_b128 v[222:225], v241 offset:1792
	s_waitcnt lgkmcnt(8)
	v_pk_fma_f32 v[206:207], v[88:89], v[230:231], v[232:233] op_sel_hi:[0,1,1] neg_lo:[1,0,0] neg_hi:[1,0,0]
	v_pk_fma_f32 v[208:209], v[88:89], v[230:231], v[234:235] op_sel:[1,0,0] neg_lo:[1,0,0] neg_hi:[1,0,0]
	v_pk_fma_f32 v[210:211], v[90:91], v[230:231], v[236:237] op_sel_hi:[0,1,1] neg_lo:[1,0,0] neg_hi:[1,0,0]
	v_pk_fma_f32 v[212:213], v[90:91], v[230:231], v[238:239] op_sel:[1,0,0] neg_lo:[1,0,0] neg_hi:[1,0,0]
	ds_read_b128 v[84:87], v240 offset:18432
	ds_read_b64 v[100:101], v242 offset:2048
	ds_read_b128 v[92:95], v240 offset:51200
	s_waitcnt lgkmcnt(7)
	v_pk_mul_f32 v[226:227], v[206:207], v[106:107] op_sel_hi:[1,0]
	v_pk_mul_f32 v[228:229], v[206:207], v[96:97] op_sel_hi:[1,0]
	v_pk_fma_f32 v[226:227], v[208:209], v[106:107], v[226:227] op_sel:[0,1,0]
	v_pk_fma_f32 v[228:229], v[208:209], v[96:97], v[228:229] op_sel:[0,1,0]
	v_pk_fma_f32 v[226:227], v[210:211], v[108:109], v[226:227] op_sel_hi:[1,0,1]
	v_pk_fma_f32 v[228:229], v[210:211], v[98:99], v[228:229] op_sel_hi:[1,0,1]
	v_pk_fma_f32 v[226:227], v[212:213], v[108:109], v[226:227] op_sel:[0,1,0]
	v_pk_fma_f32 v[228:229], v[212:213], v[98:99], v[228:229] op_sel:[0,1,0]
	v_pk_mul_f32 v[232:233], v[118:119], v[114:115] op_sel_hi:[1,0]
	ds_write_b64 v217, v[228:229] offset:3456
	v_add_f32_dpp v230, v227, v226 row_ror:8 row_mask:0xf bank_mask:0xf
	v_pk_mul_f32 v[234:235], v[118:119], v[114:115] op_sel:[0,1]
	v_pk_mul_f32 v[236:237], v[118:119], v[116:117] op_sel_hi:[1,0]
	v_add_f32_dpp v230, v230, v230 quad_perm:[1,0,3,2] row_mask:0xf bank_mask:0xf
	v_pk_mul_f32 v[238:239], v[118:119], v[116:117] op_sel:[0,1]
	ds_read_b128 v[80:83], v240 offset:2048
	v_add_f32_dpp v230, v230, v230 quad_perm:[2,3,0,1] row_mask:0xf bank_mask:0xf
	s_waitcnt lgkmcnt(7)
; template <int CTRL> __device__ __forceinline__ float dppf(float x) { return __builtin_bit_cast(float, __builtin_amdgcn_update_dpp(0, __builtin_bit_cast(int, x), CTRL, 0xF, 0xF, false)); }
; __device__ __forceinline__ void phase_rwkv_scan(const Fr& F, int jr) {
;     ...
;                 for (int pg = 0; pg < 64; pg += 16) {
; #pragma unroll
;                     for (int pi = 0; pi < 16; ++pi) {
;                         const int p = pg + pi, pn = p < 63 ? p + 1 : 63;
;                         const f32x4 w4n = PW[pn * 16], k4n = PW[1024 + pn * 16], b4n = PW[2048 + pn * 16], d4n = PW[3072 + pn * 16], r4n = PR[pn * 16];
;                         const float vvn = PV[pn * 32];
;                         f32x2 t = S01 * k4.xy; t = S23 * k4.zw + t; float sa = t.x + t.y;
;                         sa += dppf<0x128>(sa);
;                         const f32x2 dv01 = d4.xy * vv, dv23 = d4.zw * vv;
;                         sa += dppf<0x124>(sa);
;                         const f32x2 e01 = S01 * w4.xy + dv01;
;                         sa += dppf<0x122>(sa);
;                         const f32x2 e23 = S23 * w4.zw + dv23;
;                         sa += dppf<0x121>(sa);
;                         S01 = e01 - b4.xy * sa; S23 = e23 - b4.zw * sa;
;                         f32x2 u = S01 * r4.xy; u = S23 * r4.zw + u;
;                         PY[pi * 64] = u.x + u.y;
;                         w4 = w4n; k4 = k4n; b4 = b4n; d4 = d4n; r4 = r4n; vv = vvn;
;                     }
	v_pk_fma_f32 v[232:233], v[206:207], v[102:103], v[232:233] op_sel_hi:[1,0,1]
	v_pk_fma_f32 v[234:235], v[208:209], v[102:103], v[234:235] op_sel:[0,1,0]
	v_add_f32_dpp v230, v230, v230 row_half_mirror row_mask:0xf bank_mask:0xf
	v_pk_fma_f32 v[236:237], v[210:211], v[104:105], v[236:237] op_sel_hi:[1,0,1]
	v_pk_fma_f32 v[238:239], v[212:213], v[104:105], v[238:239] op_sel:[0,1,0]
	v_mov_b32_dpp v231, v230 row_ror:8 row_mask:0xf bank_mask:0xf
	ds_read_b128 v[88:91], v240 offset:34816
	ds_read_b128 v[96:99], v241 offset:2048
	s_waitcnt lgkmcnt(8)
	v_pk_fma_f32 v[206:207], v[110:111], v[230:231], v[232:233] op_sel_hi:[0,1,1] neg_lo:[1,0,0] neg_hi:[1,0,0]
	v_pk_fma_f32 v[208:209], v[110:111], v[230:231], v[234:235] op_sel:[1,0,0] neg_lo:[1,0,0] neg_hi:[1,0,0]
	v_pk_fma_f32 v[210:211], v[112:113], v[230:231], v[236:237] op_sel_hi:[0,1,1] neg_lo:[1,0,0] neg_hi:[1,0,0]
	v_pk_fma_f32 v[212:213], v[112:113], v[230:231], v[238:239] op_sel:[1,0,0] neg_lo:[1,0,0] neg_hi:[1,0,0]
	ds_read_b128 v[106:109], v240 offset:18688
	ds_read_b64 v[118:119], v242 offset:2304
	ds_read_b128 v[114:117], v240 offset:51456
	s_waitcnt lgkmcnt(7)
	v_pk_mul_f32 v[226:227], v[206:207], v[84:85] op_sel_hi:[1,0]
	v_pk_mul_f32 v[228:229], v[206:207], v[222:223] op_sel_hi:[1,0]
	v_pk_fma_f32 v[226:227], v[208:209], v[84:85], v[226:227] op_sel:[0,1,0]
	v_pk_fma_f32 v[228:229], v[208:209], v[222:223], v[228:229] op_sel:[0,1,0]
	v_pk_fma_f32 v[226:227], v[210:211], v[86:87], v[226:227] op_sel_hi:[1,0,1]
	v_pk_fma_f32 v[228:229], v[210:211], v[224:225], v[228:229] op_sel_hi:[1,0,1]
	v_pk_fma_f32 v[226:227], v[212:213], v[86:87], v[226:227] op_sel:[0,1,0]
	v_pk_fma_f32 v[228:229], v[212:213], v[224:225], v[228:229] op_sel:[0,1,0]
	v_pk_mul_f32 v[232:233], v[100:101], v[92:93] op_sel_hi:[1,0]
	ds_write_b64 v217, v[228:229] offset:4032
	v_add_f32_dpp v230, v227, v226 row_ror:8 row_mask:0xf bank_mask:0xf
	v_pk_mul_f32 v[234:235], v[100:101], v[92:93] op_sel:[0,1]
	v_pk_mul_f32 v[236:237], v[100:101], v[94:95] op_sel_hi:[1,0]
	v_add_f32_dpp v230, v230, v230 quad_perm:[1,0,3,2] row_mask:0xf bank_mask:0xf
	v_pk_mul_f32 v[238:239], v[100:101], v[94:95] op_sel:[0,1]
	ds_read_b128 v[102:105], v240 offset:2304
	v_add_f32_dpp v230, v230, v230 quad_perm:[2,3,0,1] row_mask:0xf bank_mask:0xf
	s_waitcnt lgkmcnt(7)
	v_pk_fma_f32 v[232:233], v[206:207], v[80:81], v[232:233] op_sel_hi:[1,0,1]
	v_pk_fma_f32 v[234:235], v[208:209], v[80:81], v[234:235] op_sel:[0,1,0]
	v_add_f32_dpp v230, v230, v230 row_half_mirror row_mask:0xf bank_mask:0xf
	v_pk_fma_f32 v[236:237], v[210:211], v[82:83], v[236:237] op_sel_hi:[1,0,1]
	v_pk_fma_f32 v[238:239], v[212:213], v[82:83], v[238:239] op_sel:[0,1,0]
	v_mov_b32_dpp v231, v230 row_ror:8 row_mask:0xf bank_mask:0xf
	ds_read_b128 v[110:113], v240 offset:35072
	ds_read_b128 v[222:225], v241 offset:2304
	s_waitcnt lgkmcnt(8)
	v_pk_fma_f32 v[206:207], v[88:89], v[230:231], v[232:233] op_sel_hi:[0,1,1] neg_lo:[1,0,0] neg_hi:[1,0,0]
	v_pk_fma_f32 v[208:209], v[88:89], v[230:231], v[234:235] op_sel:[1,0,0] neg_lo:[1,0,0] neg_hi:[1,0,0]
	v_pk_fma_f32 v[210:211], v[90:91], v[230:231], v[236:237] op_sel_hi:[0,1,1] neg_lo:[1,0,0] neg_hi:[1,0,0]
	v_pk_fma_f32 v[212:213], v[90:91], v[230:231], v[238:239] op_sel:[1,0,0] neg_lo:[1,0,0] neg_hi:[1,0,0]
	ds_read_b128 v[84:87], v240 offset:18944
	ds_read_b64 v[100:101], v242 offset:2560
	ds_read_b128 v[92:95], v240 offset:51712
	s_waitcnt lgkmcnt(7)
	v_pk_mul_f32 v[226:227], v[206:207], v[106:107] op_sel_hi:[1,0]
	v_pk_mul_f32 v[228:229], v[206:207], v[96:97] op_sel_hi:[1,0]
	v_pk_fma_f32 v[226:227], v[208:209], v[106:107], v[226:227] op_sel:[0,1,0]
	v_pk_fma_f32 v[228:229], v[208:209], v[96:97], v[228:229] op_sel:[0,1,0]
	v_pk_fma_f32 v[226:227], v[210:211], v[108:109], v[226:227] op_sel_hi:[1,0,1]
	v_pk_fma_f32 v[228:229], v[210:211], v[98:99], v[228:229] op_sel_hi:[1,0,1]
	v_pk_fma_f32 v[226:227], v[212:213], v[108:109], v[226:227] op_sel:[0,1,0]
	v_pk_fma_f32 v[228:229], v[212:213], v[98:99], v[228:229] op_sel:[0,1,0]
	v_pk_mul_f32 v[232:233], v[118:119], v[114:115] op_sel_hi:[1,0]
	ds_write_b64 v217, v[228:229] offset:4608
	v_add_f32_dpp v230, v227, v226 row_ror:8 row_mask:0xf bank_mask:0xf
	v_pk_mul_f32 v[234:235], v[118:119], v[114:115] op_sel:[0,1]
	v_pk_mul_f32 v[236:237], v[118:119], v[116:117] op_sel_hi:[1,0]
	v_add_f32_dpp v230, v230, v230 quad_perm:[1,0,3,2] row_mask:0xf bank_mask:0xf
	v_pk_mul_f32 v[238:239], v[118:119], v[116:117] op_sel:[0,1]
	ds_read_b128 v[80:83], v240 offset:2560
	v_add_f32_dpp v230, v230, v230 quad_perm:[2,3,0,1] row_mask:0xf bank_mask:0xf
	s_waitcnt lgkmcnt(7)
	v_pk_fma_f32 v[232:233], v[206:207], v[102:103], v[232:233] op_sel_hi:[1,0,1]
	v_pk_fma_f32 v[234:235], v[208:209], v[102:103], v[234:235] op_sel:[0,1,0]
	v_add_f32_dpp v230, v230, v230 row_half_mirror row_mask:0xf bank_mask:0xf
	v_pk_fma_f32 v[236:237], v[210:211], v[104:105], v[236:237] op_sel_hi:[1,0,1]
	v_pk_fma_f32 v[238:239], v[212:213], v[104:105], v[238:239] op_sel:[0,1,0]
	v_mov_b32_dpp v231, v230 row_ror:8 row_mask:0xf bank_mask:0xf
	ds_read_b128 v[88:91], v240 offset:35328
	ds_read_b128 v[96:99], v241 offset:2560
	s_waitcnt lgkmcnt(8)
	v_pk_fma_f32 v[206:207], v[110:111], v[230:231], v[232:233] op_sel_hi:[0,1,1] neg_lo:[1,0,0] neg_hi:[1,0,0]
	v_pk_fma_f32 v[208:209], v[110:111], v[230:231], v[234:235] op_sel:[1,0,0] neg_lo:[1,0,0] neg_hi:[1,0,0]
	v_pk_fma_f32 v[210:211], v[112:113], v[230:231], v[236:237] op_sel_hi:[0,1,1] neg_lo:[1,0,0] neg_hi:[1,0,0]
	v_pk_fma_f32 v[212:213], v[112:113], v[230:231], v[238:239] op_sel:[1,0,0] neg_lo:[1,0,0] neg_hi:[1,0,0]
	ds_read_b128 v[106:109], v240 offset:19200
	ds_read_b64 v[118:119], v242 offset:2816
	ds_read_b128 v[114:117], v240 offset:51968
	s_waitcnt lgkmcnt(7)
; template <int CTRL> __device__ __forceinline__ float dppf(float x) { return __builtin_bit_cast(float, __builtin_amdgcn_update_dpp(0, __builtin_bit_cast(int, x), CTRL, 0xF, 0xF, false)); }
; __device__ __forceinline__ void phase_rwkv_scan(const Fr& F, int jr) {
;     ...
;                 for (int pg = 0; pg < 64; pg += 16) {
; #pragma unroll
;                     for (int pi = 0; pi < 16; ++pi) {
;                         const int p = pg + pi, pn = p < 63 ? p + 1 : 63;
;                         const f32x4 w4n = PW[pn * 16], k4n = PW[1024 + pn * 16], b4n = PW[2048 + pn * 16], d4n = PW[3072 + pn * 16], r4n = PR[pn * 16];
;                         const float vvn = PV[pn * 32];
;                         f32x2 t = S01 * k4.xy; t = S23 * k4.zw + t; float sa = t.x + t.y;
;                         sa += dppf<0x128>(sa);
;                         const f32x2 dv01 = d4.xy * vv, dv23 = d4.zw * vv;
;                         sa += dppf<0x124>(sa);
;                         const f32x2 e01 = S01 * w4.xy + dv01;
;                         sa += dppf<0x122>(sa);
;                         const f32x2 e23 = S23 * w4.zw + dv23;
;                         sa += dppf<0x121>(sa);
;                         S01 = e01 - b4.xy * sa; S23 = e23 - b4.zw * sa;
;                         f32x2 u = S01 * r4.xy; u = S23 * r4.zw + u;
;                         PY[pi * 64] = u.x + u.y;
;                         w4 = w4n; k4 = k4n; b4 = b4n; d4 = d4n; r4 = r4n; vv = vvn;
;                     }
	v_pk_mul_f32 v[226:227], v[206:207], v[84:85] op_sel_hi:[1,0]
	v_pk_mul_f32 v[228:229], v[206:207], v[222:223] op_sel_hi:[1,0]
	v_pk_fma_f32 v[226:227], v[208:209], v[84:85], v[226:227] op_sel:[0,1,0]
	v_pk_fma_f32 v[228:229], v[208:209], v[222:223], v[228:229] op_sel:[0,1,0]
	v_pk_fma_f32 v[226:227], v[210:211], v[86:87], v[226:227] op_sel_hi:[1,0,1]
	v_pk_fma_f32 v[228:229], v[210:211], v[224:225], v[228:229] op_sel_hi:[1,0,1]
	v_pk_fma_f32 v[226:227], v[212:213], v[86:87], v[226:227] op_sel:[0,1,0]
	v_pk_fma_f32 v[228:229], v[212:213], v[224:225], v[228:229] op_sel:[0,1,0]
	v_pk_mul_f32 v[232:233], v[100:101], v[92:93] op_sel_hi:[1,0]
	ds_write_b64 v217, v[228:229] offset:5184
	v_add_f32_dpp v230, v227, v226 row_ror:8 row_mask:0xf bank_mask:0xf
	v_pk_mul_f32 v[234:235], v[100:101], v[92:93] op_sel:[0,1]
	v_pk_mul_f32 v[236:237], v[100:101], v[94:95] op_sel_hi:[1,0]
	v_add_f32_dpp v230, v230, v230 quad_perm:[1,0,3,2] row_mask:0xf bank_mask:0xf
	v_pk_mul_f32 v[238:239], v[100:101], v[94:95] op_sel:[0,1]
	ds_read_b128 v[102:105], v240 offset:2816
	v_add_f32_dpp v230, v230, v230 quad_perm:[2,3,0,1] row_mask:0xf bank_mask:0xf
	s_waitcnt lgkmcnt(7)
	v_pk_fma_f32 v[232:233], v[206:207], v[80:81], v[232:233] op_sel_hi:[1,0,1]
	v_pk_fma_f32 v[234:235], v[208:209], v[80:81], v[234:235] op_sel:[0,1,0]
	v_add_f32_dpp v230, v230, v230 row_half_mirror row_mask:0xf bank_mask:0xf
	v_pk_fma_f32 v[236:237], v[210:211], v[82:83], v[236:237] op_sel_hi:[1,0,1]
	v_pk_fma_f32 v[238:239], v[212:213], v[82:83], v[238:239] op_sel:[0,1,0]
	v_mov_b32_dpp v231, v230 row_ror:8 row_mask:0xf bank_mask:0xf
	ds_read_b128 v[110:113], v240 offset:35584
	ds_read_b128 v[222:225], v241 offset:2816
	s_waitcnt lgkmcnt(8)
	v_pk_fma_f32 v[206:207], v[88:89], v[230:231], v[232:233] op_sel_hi:[0,1,1] neg_lo:[1,0,0] neg_hi:[1,0,0]
	v_pk_fma_f32 v[208:209], v[88:89], v[230:231], v[234:235] op_sel:[1,0,0] neg_lo:[1,0,0] neg_hi:[1,0,0]
	v_pk_fma_f32 v[210:211], v[90:91], v[230:231], v[236:237] op_sel_hi:[0,1,1] neg_lo:[1,0,0] neg_hi:[1,0,0]
	v_pk_fma_f32 v[212:213], v[90:91], v[230:231], v[238:239] op_sel:[1,0,0] neg_lo:[1,0,0] neg_hi:[1,0,0]
	ds_read_b128 v[84:87], v240 offset:19456
	ds_read_b64 v[100:101], v242 offset:3072
	ds_read_b128 v[92:95], v240 offset:52224
	s_waitcnt lgkmcnt(7)
	v_pk_mul_f32 v[226:227], v[206:207], v[106:107] op_sel_hi:[1,0]
	v_pk_mul_f32 v[228:229], v[206:207], v[96:97] op_sel_hi:[1,0]
	v_pk_fma_f32 v[226:227], v[208:209], v[106:107], v[226:227] op_sel:[0,1,0]
	v_pk_fma_f32 v[228:229], v[208:209], v[96:97], v[228:229] op_sel:[0,1,0]
	v_pk_fma_f32 v[226:227], v[210:211], v[108:109], v[226:227] op_sel_hi:[1,0,1]
	v_pk_fma_f32 v[228:229], v[210:211], v[98:99], v[228:229] op_sel_hi:[1,0,1]
	v_pk_fma_f32 v[226:227], v[212:213], v[108:109], v[226:227] op_sel:[0,1,0]
	v_pk_fma_f32 v[228:229], v[212:213], v[98:99], v[228:229] op_sel:[0,1,0]
	v_pk_mul_f32 v[232:233], v[118:119], v[114:115] op_sel_hi:[1,0]
	ds_write_b64 v217, v[228:229] offset:5760
	v_add_f32_dpp v230, v227, v226 row_ror:8 row_mask:0xf bank_mask:0xf
	v_pk_mul_f32 v[234:235], v[118:119], v[114:115] op_sel:[0,1]
	v_pk_mul_f32 v[236:237], v[118:119], v[116:117] op_sel_hi:[1,0]
	v_add_f32_dpp v230, v230, v230 quad_perm:[1,0,3,2] row_mask:0xf bank_mask:0xf
	v_pk_mul_f32 v[238:239], v[118:119], v[116:117] op_sel:[0,1]
	ds_read_b128 v[80:83], v240 offset:3072
	v_add_f32_dpp v230, v230, v230 quad_perm:[2,3,0,1] row_mask:0xf bank_mask:0xf
	s_waitcnt lgkmcnt(7)
	v_pk_fma_f32 v[232:233], v[206:207], v[102:103], v[232:233] op_sel_hi:[1,0,1]
	v_pk_fma_f32 v[234:235], v[208:209], v[102:103], v[234:235] op_sel:[0,1,0]
	v_add_f32_dpp v230, v230, v230 row_half_mirror row_mask:0xf bank_mask:0xf
	v_pk_fma_f32 v[236:237], v[210:211], v[104:105], v[236:237] op_sel_hi:[1,0,1]
	v_pk_fma_f32 v[238:239], v[212:213], v[104:105], v[238:239] op_sel:[0,1,0]
	v_mov_b32_dpp v231, v230 row_ror:8 row_mask:0xf bank_mask:0xf
	ds_read_b128 v[88:91], v240 offset:35840
	ds_read_b128 v[96:99], v241 offset:3072
	s_waitcnt lgkmcnt(8)
	v_pk_fma_f32 v[206:207], v[110:111], v[230:231], v[232:233] op_sel_hi:[0,1,1] neg_lo:[1,0,0] neg_hi:[1,0,0]
	v_pk_fma_f32 v[208:209], v[110:111], v[230:231], v[234:235] op_sel:[1,0,0] neg_lo:[1,0,0] neg_hi:[1,0,0]
	v_pk_fma_f32 v[210:211], v[112:113], v[230:231], v[236:237] op_sel_hi:[0,1,1] neg_lo:[1,0,0] neg_hi:[1,0,0]
	v_pk_fma_f32 v[212:213], v[112:113], v[230:231], v[238:239] op_sel:[1,0,0] neg_lo:[1,0,0] neg_hi:[1,0,0]
	ds_read_b128 v[106:109], v240 offset:19712
	ds_read_b64 v[118:119], v242 offset:3328
	ds_read_b128 v[114:117], v240 offset:52480
	s_waitcnt lgkmcnt(7)
	v_pk_mul_f32 v[226:227], v[206:207], v[84:85] op_sel_hi:[1,0]
	v_pk_mul_f32 v[228:229], v[206:207], v[222:223] op_sel_hi:[1,0]
	v_pk_fma_f32 v[226:227], v[208:209], v[84:85], v[226:227] op_sel:[0,1,0]
	v_pk_fma_f32 v[228:229], v[208:209], v[222:223], v[228:229] op_sel:[0,1,0]
	v_pk_fma_f32 v[226:227], v[210:211], v[86:87], v[226:227] op_sel_hi:[1,0,1]
	v_pk_fma_f32 v[228:229], v[210:211], v[224:225], v[228:229] op_sel_hi:[1,0,1]
	v_pk_fma_f32 v[226:227], v[212:213], v[86:87], v[226:227] op_sel:[0,1,0]
	v_pk_fma_f32 v[228:229], v[212:213], v[224:225], v[228:229] op_sel:[0,1,0]
	v_pk_mul_f32 v[232:233], v[100:101], v[92:93] op_sel_hi:[1,0]
	ds_write_b64 v217, v[228:229] offset:6336
	v_add_f32_dpp v230, v227, v226 row_ror:8 row_mask:0xf bank_mask:0xf
	v_pk_mul_f32 v[234:235], v[100:101], v[92:93] op_sel:[0,1]
	v_pk_mul_f32 v[236:237], v[100:101], v[94:95] op_sel_hi:[1,0]
	v_add_f32_dpp v230, v230, v230 quad_perm:[1,0,3,2] row_mask:0xf bank_mask:0xf
	v_pk_mul_f32 v[238:239], v[100:101], v[94:95] op_sel:[0,1]
	ds_read_b128 v[102:105], v240 offset:3328
	v_add_f32_dpp v230, v230, v230 quad_perm:[2,3,0,1] row_mask:0xf bank_mask:0xf
	s_waitcnt lgkmcnt(7)
; template <int CTRL> __device__ __forceinline__ float dppf(float x) { return __builtin_bit_cast(float, __builtin_amdgcn_update_dpp(0, __builtin_bit_cast(int, x), CTRL, 0xF, 0xF, false)); }
; __device__ __forceinline__ void phase_rwkv_scan(const Fr& F, int jr) {
;     ...
;                 for (int pg = 0; pg < 64; pg += 16) {
; #pragma unroll
;                     for (int pi = 0; pi < 16; ++pi) {
;                         const int p = pg + pi, pn = p < 63 ? p + 1 : 63;
;                         const f32x4 w4n = PW[pn * 16], k4n = PW[1024 + pn * 16], b4n = PW[2048 + pn * 16], d4n = PW[3072 + pn * 16], r4n = PR[pn * 16];
;                         const float vvn = PV[pn * 32];
;                         f32x2 t = S01 * k4.xy; t = S23 * k4.zw + t; float sa = t.x + t.y;
;                         sa += dppf<0x128>(sa);
;                         const f32x2 dv01 = d4.xy * vv, dv23 = d4.zw * vv;
;                         sa += dppf<0x124>(sa);
;                         const f32x2 e01 = S01 * w4.xy + dv01;
;                         sa += dppf<0x122>(sa);
;                         const f32x2 e23 = S23 * w4.zw + dv23;
;                         sa += dppf<0x121>(sa);
;                         S01 = e01 - b4.xy * sa; S23 = e23 - b4.zw * sa;
;                         f32x2 u = S01 * r4.xy; u = S23 * r4.zw + u;
;                         PY[pi * 64] = u.x + u.y;
;                         w4 = w4n; k4 = k4n; b4 = b4n; d4 = d4n; r4 = r4n; vv = vvn;
;                     }
	v_pk_fma_f32 v[232:233], v[206:207], v[80:81], v[232:233] op_sel_hi:[1,0,1]
	v_pk_fma_f32 v[234:235], v[208:209], v[80:81], v[234:235] op_sel:[0,1,0]
	v_add_f32_dpp v230, v230, v230 row_half_mirror row_mask:0xf bank_mask:0xf
	v_pk_fma_f32 v[236:237], v[210:211], v[82:83], v[236:237] op_sel_hi:[1,0,1]
	v_pk_fma_f32 v[238:239], v[212:213], v[82:83], v[238:239] op_sel:[0,1,0]
	v_mov_b32_dpp v231, v230 row_ror:8 row_mask:0xf bank_mask:0xf
	ds_read_b128 v[110:113], v240 offset:36096
	ds_read_b128 v[222:225], v241 offset:3328
	s_waitcnt lgkmcnt(8)
	v_pk_fma_f32 v[206:207], v[88:89], v[230:231], v[232:233] op_sel_hi:[0,1,1] neg_lo:[1,0,0] neg_hi:[1,0,0]
	v_pk_fma_f32 v[208:209], v[88:89], v[230:231], v[234:235] op_sel:[1,0,0] neg_lo:[1,0,0] neg_hi:[1,0,0]
	v_pk_fma_f32 v[210:211], v[90:91], v[230:231], v[236:237] op_sel_hi:[0,1,1] neg_lo:[1,0,0] neg_hi:[1,0,0]
	v_pk_fma_f32 v[212:213], v[90:91], v[230:231], v[238:239] op_sel:[1,0,0] neg_lo:[1,0,0] neg_hi:[1,0,0]
	ds_read_b128 v[84:87], v240 offset:19968
	ds_read_b64 v[100:101], v242 offset:3584
	ds_read_b128 v[92:95], v240 offset:52736
	s_waitcnt lgkmcnt(7)
	v_pk_mul_f32 v[226:227], v[206:207], v[106:107] op_sel_hi:[1,0]
	v_pk_mul_f32 v[228:229], v[206:207], v[96:97] op_sel_hi:[1,0]
	v_pk_fma_f32 v[226:227], v[208:209], v[106:107], v[226:227] op_sel:[0,1,0]
	v_pk_fma_f32 v[228:229], v[208:209], v[96:97], v[228:229] op_sel:[0,1,0]
	v_pk_fma_f32 v[226:227], v[210:211], v[108:109], v[226:227] op_sel_hi:[1,0,1]
	v_pk_fma_f32 v[228:229], v[210:211], v[98:99], v[228:229] op_sel_hi:[1,0,1]
	v_pk_fma_f32 v[226:227], v[212:213], v[108:109], v[226:227] op_sel:[0,1,0]
	v_pk_fma_f32 v[228:229], v[212:213], v[98:99], v[228:229] op_sel:[0,1,0]
	v_pk_mul_f32 v[232:233], v[118:119], v[114:115] op_sel_hi:[1,0]
	ds_write_b64 v217, v[228:229] offset:6912
	v_add_f32_dpp v230, v227, v226 row_ror:8 row_mask:0xf bank_mask:0xf
	v_pk_mul_f32 v[234:235], v[118:119], v[114:115] op_sel:[0,1]
	v_pk_mul_f32 v[236:237], v[118:119], v[116:117] op_sel_hi:[1,0]
	v_add_f32_dpp v230, v230, v230 quad_perm:[1,0,3,2] row_mask:0xf bank_mask:0xf
	v_pk_mul_f32 v[238:239], v[118:119], v[116:117] op_sel:[0,1]
	ds_read_b128 v[80:83], v240 offset:3584
	v_add_f32_dpp v230, v230, v230 quad_perm:[2,3,0,1] row_mask:0xf bank_mask:0xf
	s_waitcnt lgkmcnt(7)
	v_pk_fma_f32 v[232:233], v[206:207], v[102:103], v[232:233] op_sel_hi:[1,0,1]
	v_pk_fma_f32 v[234:235], v[208:209], v[102:103], v[234:235] op_sel:[0,1,0]
	v_add_f32_dpp v230, v230, v230 row_half_mirror row_mask:0xf bank_mask:0xf
	v_pk_fma_f32 v[236:237], v[210:211], v[104:105], v[236:237] op_sel_hi:[1,0,1]
	v_pk_fma_f32 v[238:239], v[212:213], v[104:105], v[238:239] op_sel:[0,1,0]
	v_mov_b32_dpp v231, v230 row_ror:8 row_mask:0xf bank_mask:0xf
	ds_read_b128 v[88:91], v240 offset:36352
	ds_read_b128 v[96:99], v241 offset:3584
	s_waitcnt lgkmcnt(8)
	v_pk_fma_f32 v[206:207], v[110:111], v[230:231], v[232:233] op_sel_hi:[0,1,1] neg_lo:[1,0,0] neg_hi:[1,0,0]
	v_pk_fma_f32 v[208:209], v[110:111], v[230:231], v[234:235] op_sel:[1,0,0] neg_lo:[1,0,0] neg_hi:[1,0,0]
	v_pk_fma_f32 v[210:211], v[112:113], v[230:231], v[236:237] op_sel_hi:[0,1,1] neg_lo:[1,0,0] neg_hi:[1,0,0]
	v_pk_fma_f32 v[212:213], v[112:113], v[230:231], v[238:239] op_sel:[1,0,0] neg_lo:[1,0,0] neg_hi:[1,0,0]
	ds_read_b128 v[106:109], v240 offset:20224
	ds_read_b64 v[118:119], v242 offset:3840
	ds_read_b128 v[114:117], v240 offset:52992
	s_waitcnt lgkmcnt(7)
	v_pk_mul_f32 v[226:227], v[206:207], v[84:85] op_sel_hi:[1,0]
	v_pk_mul_f32 v[228:229], v[206:207], v[222:223] op_sel_hi:[1,0]
	v_pk_fma_f32 v[226:227], v[208:209], v[84:85], v[226:227] op_sel:[0,1,0]
	v_pk_fma_f32 v[228:229], v[208:209], v[222:223], v[228:229] op_sel:[0,1,0]
	v_pk_fma_f32 v[226:227], v[210:211], v[86:87], v[226:227] op_sel_hi:[1,0,1]
	v_pk_fma_f32 v[228:229], v[210:211], v[224:225], v[228:229] op_sel_hi:[1,0,1]
	v_pk_fma_f32 v[226:227], v[212:213], v[86:87], v[226:227] op_sel:[0,1,0]
	v_pk_fma_f32 v[228:229], v[212:213], v[224:225], v[228:229] op_sel:[0,1,0]
	v_pk_mul_f32 v[232:233], v[100:101], v[92:93] op_sel_hi:[1,0]
	ds_write_b64 v217, v[228:229] offset:7488
	v_add_f32_dpp v230, v227, v226 row_ror:8 row_mask:0xf bank_mask:0xf
	v_pk_mul_f32 v[234:235], v[100:101], v[92:93] op_sel:[0,1]
	v_pk_mul_f32 v[236:237], v[100:101], v[94:95] op_sel_hi:[1,0]
	v_add_f32_dpp v230, v230, v230 quad_perm:[1,0,3,2] row_mask:0xf bank_mask:0xf
	v_pk_mul_f32 v[238:239], v[100:101], v[94:95] op_sel:[0,1]
	ds_read_b128 v[102:105], v240 offset:3840
	v_add_f32_dpp v230, v230, v230 quad_perm:[2,3,0,1] row_mask:0xf bank_mask:0xf
	s_waitcnt lgkmcnt(7)
	v_pk_fma_f32 v[232:233], v[206:207], v[80:81], v[232:233] op_sel_hi:[1,0,1]
	v_pk_fma_f32 v[234:235], v[208:209], v[80:81], v[234:235] op_sel:[0,1,0]
	v_add_f32_dpp v230, v230, v230 row_half_mirror row_mask:0xf bank_mask:0xf
	v_pk_fma_f32 v[236:237], v[210:211], v[82:83], v[236:237] op_sel_hi:[1,0,1]
	v_pk_fma_f32 v[238:239], v[212:213], v[82:83], v[238:239] op_sel:[0,1,0]
	v_mov_b32_dpp v231, v230 row_ror:8 row_mask:0xf bank_mask:0xf
	ds_read_b128 v[110:113], v240 offset:36608
	ds_read_b128 v[222:225], v241 offset:3840
	s_waitcnt lgkmcnt(8)
; __device__ __forceinline__ unsigned f2bf(float f) { unsigned u = __builtin_bit_cast(unsigned, f); return (u + 0x7fffu + ((u >> 16) & 1u)) >> 16; }
; #define LDS_BAR() asm volatile("s_waitcnt lgkmcnt(0)\n\ts_barrier" ::: "memory")
; __device__ __forceinline__ void phase_rwkv_scan(const Fr& F, int jr) {
;     ...
;                 for (int pg = 0; pg < 64; pg += 16) {
; #pragma unroll
;                     for (int pi = 0; pi < 16; ++pi) {
;                         const int p = pg + pi, pn = p < 63 ? p + 1 : 63;
;                         const f32x4 w4n = PW[pn * 16], k4n = PW[1024 + pn * 16], b4n = PW[2048 + pn * 16], d4n = PW[3072 + pn * 16], r4n = PR[pn * 16];
;                         const float vvn = PV[pn * 32];
;                         f32x2 t = S01 * k4.xy; t = S23 * k4.zw + t; float sa = t.x + t.y;
;                         sa += dppf<0x128>(sa);
;                         const f32x2 dv01 = d4.xy * vv, dv23 = d4.zw * vv;
;                         sa += dppf<0x124>(sa);
;                         const f32x2 e01 = S01 * w4.xy + dv01;
;                         sa += dppf<0x122>(sa);
;                         const f32x2 e23 = S23 * w4.zw + dv23;
;                         sa += dppf<0x121>(sa);
;                         S01 = e01 - b4.xy * sa; S23 = e23 - b4.zw * sa;
;                         f32x2 u = S01 * r4.xy; u = S23 * r4.zw + u;
;                         PY[pi * 64] = u.x + u.y;
;                         w4 = w4n; k4 = k4n; b4 = b4n; d4 = d4n; r4 = r4n; vv = vvn;
;                     }
;                     asm volatile("s_waitcnt lgkmcnt(0)" ::: "memory");
;                     {
;                         const int j = lane >> 2, q = lane & 3; const float* yp = Ypw + j * 64 + q * 16;
;                         const f32x4 a0 = *(const f32x4*)yp, a1 = *(const f32x4*)(yp + 4), a2 = *(const f32x4*)(yp + 8), a3 = *(const f32x4*)(yp + 12);
;                         const f32x4 ssum = (a0 + a1) + (a2 + a3); const float yv = (ssum.x + ssum.y) + (ssum.z + ssum.w);
;                         const size_t row = (size_t)b * TB + tokof(s, chunk * 64 + pg + j);
;                         Yb[row * D + h * 64 + 32 * half + 4 * wave + q] = (bf16)f2bf(yv);
;                     }
;                     asm volatile("s_waitcnt lgkmcnt(0)" ::: "memory");
;                 }
;             }
;             LDS_BAR();
;         }
;         LDS_BAR();
;     }
	v_pk_fma_f32 v[206:207], v[88:89], v[230:231], v[232:233] op_sel_hi:[0,1,1] neg_lo:[1,0,0] neg_hi:[1,0,0]
	v_pk_fma_f32 v[208:209], v[88:89], v[230:231], v[234:235] op_sel:[1,0,0] neg_lo:[1,0,0] neg_hi:[1,0,0]
	v_pk_fma_f32 v[210:211], v[90:91], v[230:231], v[236:237] op_sel_hi:[0,1,1] neg_lo:[1,0,0] neg_hi:[1,0,0]
	v_pk_fma_f32 v[212:213], v[90:91], v[230:231], v[238:239] op_sel:[1,0,0] neg_lo:[1,0,0] neg_hi:[1,0,0]
	ds_read_b128 v[84:87], v240 offset:20480
	ds_read_b64 v[100:101], v242 offset:4096
	ds_read_b128 v[92:95], v240 offset:53248
	s_waitcnt lgkmcnt(7)
	v_pk_mul_f32 v[226:227], v[206:207], v[106:107] op_sel_hi:[1,0]
	v_pk_mul_f32 v[228:229], v[206:207], v[96:97] op_sel_hi:[1,0]
	v_pk_fma_f32 v[226:227], v[208:209], v[106:107], v[226:227] op_sel:[0,1,0]
	v_pk_fma_f32 v[228:229], v[208:209], v[96:97], v[228:229] op_sel:[0,1,0]
	v_pk_fma_f32 v[226:227], v[210:211], v[108:109], v[226:227] op_sel_hi:[1,0,1]
	v_pk_fma_f32 v[228:229], v[210:211], v[98:99], v[228:229] op_sel_hi:[1,0,1]
	v_pk_fma_f32 v[226:227], v[212:213], v[108:109], v[226:227] op_sel:[0,1,0]
	v_pk_fma_f32 v[228:229], v[212:213], v[98:99], v[228:229] op_sel:[0,1,0]
	v_pk_mul_f32 v[232:233], v[118:119], v[114:115] op_sel_hi:[1,0]
	ds_write_b64 v217, v[228:229] offset:8064
	v_add_f32_dpp v230, v227, v226 row_ror:8 row_mask:0xf bank_mask:0xf
	v_pk_mul_f32 v[234:235], v[118:119], v[114:115] op_sel:[0,1]
	v_pk_mul_f32 v[236:237], v[118:119], v[116:117] op_sel_hi:[1,0]
	v_add_f32_dpp v230, v230, v230 quad_perm:[1,0,3,2] row_mask:0xf bank_mask:0xf
	v_pk_mul_f32 v[238:239], v[118:119], v[116:117] op_sel:[0,1]
	ds_read_b128 v[80:83], v240 offset:4096
	v_add_f32_dpp v230, v230, v230 quad_perm:[2,3,0,1] row_mask:0xf bank_mask:0xf
	s_waitcnt lgkmcnt(7)
	v_pk_fma_f32 v[232:233], v[206:207], v[102:103], v[232:233] op_sel_hi:[1,0,1]
	v_pk_fma_f32 v[234:235], v[208:209], v[102:103], v[234:235] op_sel:[0,1,0]
	v_add_f32_dpp v230, v230, v230 row_half_mirror row_mask:0xf bank_mask:0xf
	v_pk_fma_f32 v[236:237], v[210:211], v[104:105], v[236:237] op_sel_hi:[1,0,1]
	v_pk_fma_f32 v[238:239], v[212:213], v[104:105], v[238:239] op_sel:[0,1,0]
	v_mov_b32_dpp v231, v230 row_ror:8 row_mask:0xf bank_mask:0xf
	ds_read_b128 v[88:91], v240 offset:36864
	ds_read_b128 v[96:99], v241 offset:4096
	s_waitcnt lgkmcnt(8)
	v_pk_fma_f32 v[206:207], v[110:111], v[230:231], v[232:233] op_sel_hi:[0,1,1] neg_lo:[1,0,0] neg_hi:[1,0,0]
	v_pk_fma_f32 v[208:209], v[110:111], v[230:231], v[234:235] op_sel:[1,0,0] neg_lo:[1,0,0] neg_hi:[1,0,0]
	v_pk_fma_f32 v[210:211], v[112:113], v[230:231], v[236:237] op_sel_hi:[0,1,1] neg_lo:[1,0,0] neg_hi:[1,0,0]
	v_pk_fma_f32 v[212:213], v[112:113], v[230:231], v[238:239] op_sel:[1,0,0] neg_lo:[1,0,0] neg_hi:[1,0,0]
	s_waitcnt lgkmcnt(7)
	v_pk_mul_f32 v[228:229], v[206:207], v[222:223] op_sel_hi:[1,0]
	v_add_u32_e32 v243, s90, v219
	v_pk_fma_f32 v[228:229], v[208:209], v[222:223], v[228:229] op_sel:[0,1,0]
	v_lshl_add_u32 v243, v243, 11, v220
	v_pk_fma_f32 v[228:229], v[210:211], v[224:225], v[228:229] op_sel_hi:[1,0,1]
	v_add_u32_e32 v240, 0x1000, v240
	v_pk_fma_f32 v[228:229], v[212:213], v[224:225], v[228:229] op_sel:[0,1,0]
	v_add_u32_e32 v241, 0x1000, v241
	v_add_u32_e32 v242, 0x1000, v242
	s_waitcnt lgkmcnt(0)
	ds_write_b64 v217, v[228:229] offset:8640
	ds_read_b128 v[102:105], v218 offset:0
	ds_read_b128 v[106:109], v218 offset:16
	ds_read_b128 v[110:113], v218 offset:32
	ds_read_b128 v[114:117], v218 offset:48
	ds_read_b128 v[222:225], v218 offset:64
	ds_read_b128 v[232:235], v218 offset:80
	ds_read_b128 v[236:239], v218 offset:96
	ds_read_b128 v[226:229], v218 offset:112
	s_waitcnt lgkmcnt(6)
	v_pk_add_f32 v[102:103], v[102:103], v[104:105]
	v_pk_add_f32 v[106:107], v[106:107], v[108:109]
	s_waitcnt lgkmcnt(4)
	v_pk_add_f32 v[110:111], v[110:111], v[112:113]
	v_pk_add_f32 v[114:115], v[114:115], v[116:117]
	v_pk_add_f32 v[102:103], v[102:103], v[106:107]
	s_waitcnt lgkmcnt(2)
	v_pk_add_f32 v[222:223], v[222:223], v[224:225]
	v_pk_add_f32 v[232:233], v[232:233], v[234:235]
	v_pk_add_f32 v[110:111], v[110:111], v[114:115]
	s_waitcnt lgkmcnt(0)
	v_pk_add_f32 v[236:237], v[236:237], v[238:239]
	v_pk_add_f32 v[226:227], v[226:227], v[228:229]
	v_pk_add_f32 v[222:223], v[222:223], v[232:233]
	v_pk_add_f32 v[102:103], v[102:103], v[110:111]
	v_pk_add_f32 v[236:237], v[236:237], v[226:227]
	s_add_i32 s87, s87, 1
	v_pk_add_f32 v[222:223], v[222:223], v[236:237]
	s_add_i32 s90, s90, s94
	v_pk_add_f32 v[102:103], v[102:103], v[222:223] op_sel:[0,1] op_sel_hi:[1,0]
	s_cmp_lt_u32 s87, 4
	v_cvt_pk_bf16_f32 v244, v102, v103
	s_nop 0
	global_store_dword v243, v244, s[88:89]
	s_waitcnt lgkmcnt(0)
	s_cbranch_scc1 .Lrw0_group
.Lrw0_skip:
	s_waitcnt lgkmcnt(0)
	s_barrier
	v_add_u32_e32 v151, 64, v151
	v_subrev_u32_e32 v149, 64, v149
	s_cmpk_eq_i32 s10, 0x44
	s_mov_b32 s56, s10
	s_cbranch_scc0 .LBB0_556
	s_waitcnt lgkmcnt(0)
	s_barrier
	s_add_i32 s3, s3, s30
	s_cmpk_gt_i32 s3, 0xff
	s_cbranch_scc0 .LBB0_555
	v_mov_b32_e32 v1, s34
	v_mov_b32_e32 v2, s35

; __device__ __forceinline__ void phase_rwkv_scan(const Fr& F, int jr) {
;     ...
;     for (int task = bxcd; task < 256; task += gridDim.x) {
;         const int half = task & 1, h = (task >> 1) & 15, b = (task >> 5) & 3, s = task >> 7;
;         bf16* Yb = F.R(s);
;         const float* w0 = F.a->in[9] + (size_t)(jr * 2 + s) * D + h * 64; const float* a0 = F.a->in[12] + (size_t)(jr * 2 + s) * D + h * 64;
;         const float* kkw = F.a->in[15] + (size_t)jr * D + h * 64; const float* kaw = F.a->in[16] + (size_t)jr * D + h * 64;
;         f32x2 S01 = {0.f, 0.f}, S23 = {0.f, 0.f};
;         const int ks = 4 * l15, rloc = 4 * wave + lq;
;         const int pt = wave & 3, ht0 = (wave >> 2) * 2;
;         const int p1 = pt * 16 + l15;
;         const int p2 = tid >> 3, j8 = tid & 7, hk0 = 8 * j8;
;         bf16x8 Bw[2][2], Ba[2][2]; float w0v[2], a0v[2];
; #pragma unroll
;         for (int hh = 0; hh < 2; ++hh) { const int hk = (ht0 + hh) * 16 + l15, e = h * 64 + hk; w0v[hh] = w0[hk]; a0v[hh] = a0[hk];
; #pragma unroll
;             for (int kst = 0; kst < 2; ++kst) { Bw[hh][kst] = *(const bf16x8*)(L2T + ((size_t)s * D + e) * 64 + 32 * kst + 8 * lq); Ba[hh][kst] = *(const bf16x8*)(L2T + ((size_t)(2 + s) * D + e) * 64 + 32 * kst + 8 * lq); } }
;         float kkc[8], kac[8], rkc[8];
; #pragma unroll
;         for (int i = 0; i < 8; ++i) { kkc[i] = kkw[hk0 + i]; kac[i] = kaw[hk0 + i]; rkc[i] = F.a->in[17][(size_t)jr * D + h * 64 + hk0 + i]; }
;         float* Bon = (float*)(F.ws + OFF_R0 + 6 * RSZ + 16 * MiB);
;         bf16x8 Aw[2], Aa[2]; u32x4 kw, rw; u32x2 vw;
;         {   const size_t row1 = (size_t)b * TB + tokof(s, p1), row2 = (size_t)b * TB + tokof(s, p2);
; #pragma unroll
;             for (int kst = 0; kst < 2; ++kst) { Aw[kst] = *(const bf16x8*)(LM + row1 * 256 + 64 * s + 32 * kst + 8 * lq); Aa[kst] = *(const bf16x8*)(LM + row1 * 256 + 128 + 64 * s + 32 * kst + 8 * lq); }
;             kw = *(const u32x4*)(Kb + row2 * D + h * 64 + hk0); rw = *(const u32x4*)(Rb + row2 * D + h * 64 + hk0); vw = *(const u32x2*)(Vb + row2 * D + h * 64 + 32 * half + 4 * j8); }
;     ...
;                 float* Ypw = Yp + wave * 1024;
;                 unsigned a1 = (unsigned)(size_t)(__attribute__((address_space(3))) float*)(Wv + ks), a2 = (unsigned)(size_t)(__attribute__((address_space(3))) float*)(Rr + ks),
.LBB0_2533:
	s_ashr_i32 s8, s3, 7
	s_add_i32 s6, s8, 2
	s_ashr_i32 s7, s6, 31
	s_bfe_u32 s55, s3, 0x40001
	s_ashr_i32 s9, s8, 31
	s_lshl_b64 s[10:11], s[6:7], 12
	s_add_u32 s44, s22, s10
	s_addc_u32 s45, s23, s11
	s_lshl_b32 s60, s55, 6
	s_lshl_b32 s20, s55, 8
	s_add_u32 s44, s44, s20
	s_addc_u32 s45, s45, 0
	s_add_u32 s10, s24, s10
	s_addc_u32 s11, s25, s11
	s_add_u32 s10, s10, s20
	s_addc_u32 s11, s11, 0
	s_lshl_b64 s[6:7], s[6:7], 17
	s_mul_i32 s59, s8, 0x2200000
	s_lshl_b64 s[56:57], s[8:9], 17
	v_lshl_add_u64 v[18:19], v[124:125], 0, s[6:7]
	v_add_u32_e32 v122, s60, v136
	s_bfe_u32 s6, s3, 0x20005
	s_mul_hi_i32 s58, s8, 0x2200000
	v_lshlrev_b64 v[0:1], 7, v[122:123]
	v_add_u32_e32 v122, s60, v176
	v_or_b32_e32 v32, s60, v120
	s_add_u32 s60, s46, s59
	s_addc_u32 s61, s47, s58
	v_lshl_add_u64 v[16:17], v[124:125], 0, s[56:57]
	s_cmpk_lt_u32 s3, 0x80
	v_lshlrev_b32_e32 v20, 2, v136
	v_lshl_add_u64 v[4:5], v[16:17], 0, v[0:1]
	v_lshl_add_u64 v[12:13], v[18:19], 0, v[0:1]
	v_lshl_add_u64 v[44:45], v[138:139], 0, s[20:21]
	v_lshl_add_u64 v[52:53], v[140:141], 0, s[20:21]
	s_mul_i32 s20, s6, 0x1100
	s_cselect_b64 s[6:7], -1, 0
	global_load_dwordx4 v[0:3], v[4:5], off
	s_nop 0
	global_load_dwordx4 v[4:7], v[4:5], off offset:64
	s_nop 0
	global_load_dwordx4 v[8:11], v[12:13], off
	s_nop 0
	global_load_dwordx4 v[12:15], v[12:13], off offset:64
	s_nop 0
	global_load_dword v192, v20, s[44:45]
	global_load_dword v193, v20, s[10:11]
	global_load_dword v194, v20, s[10:11] offset:64
	global_load_dword v195, v20, s[44:45] offset:64
	v_lshlrev_b64 v[20:21], 7, v[122:123]
	v_lshlrev_b32_e32 v122, 2, v32
	s_waitcnt vmcnt(0)
	v_cndmask_b32_e64 v56, v167, v121, s[6:7]
	v_lshl_add_u64 v[32:33], s[38:39], 0, v[122:123]
	v_or_b32_e32 v56, s20, v56
	v_cndmask_b32_e64 v72, v168, v129, s[6:7]
	s_lshl_b32 s8, s8, 6
	v_lshl_add_u64 v[36:37], v[32:33], 0, s[42:43]
	v_add_co_u32_e32 v32, vcc, s50, v32
	v_lshlrev_b32_e32 v122, 9, v56
	s_ashr_i32 s9, s8, 31
	v_or_b32_e32 v72, s20, v72
	v_lshl_add_u64 v[22:23], v[16:17], 0, v[20:21]
	v_lshl_add_u64 v[28:29], v[18:19], 0, v[20:21]
	v_addc_co_u32_e32 v33, vcc, 0, v33, vcc
	v_lshl_add_u64 v[56:57], s[18:19], 0, v[122:123]
	s_lshl_b64 s[10:11], s[8:9], 1
	v_lshlrev_b32_e32 v122, 11, v72
	global_load_dwordx4 v[16:19], v[22:23], off
	s_nop 0
	global_load_dwordx4 v[20:23], v[22:23], off offset:64
	s_nop 0
	global_load_dwordx4 v[24:27], v[28:29], off
	s_nop 0
	global_load_dwordx4 v[28:31], v[28:29], off offset:64
	s_nop 0
	global_load_dwordx4 v[32:35], v[32:33], off
	s_nop 0
	global_load_dwordx4 v[36:39], v[36:37], off offset:16
	s_nop 0
	global_load_dwordx4 v[40:43], v[44:45], off offset:16
	s_nop 0
	global_load_dwordx4 v[44:47], v[44:45], off
	s_nop 0
	global_load_dwordx4 v[48:51], v[52:53], off offset:16
	s_nop 0
	global_load_dwordx4 v[52:55], v[52:53], off
	v_lshl_add_u64 v[56:57], v[56:57], 0, s[10:11]
	v_mov_b32_e32 v145, v123
	s_lshl_b32 s56, s55, 7
	s_mov_b32 s57, s21
	v_lshl_add_u64 v[80:81], s[16:17], 0, v[122:123]
	s_lshl_b32 s8, s3, 6
	v_lshl_add_u64 v[68:69], v[56:57], 0, v[144:145]
	v_lshl_add_u64 v[72:73], s[14:15], 0, v[122:123]
	v_lshl_add_u64 v[76:77], s[12:13], 0, v[122:123]
	v_lshl_add_u64 v[80:81], v[80:81], 0, s[56:57]
	s_and_b32 s58, s8, 64
	s_mov_b32 s59, s21
	global_load_dwordx4 v[56:59], v[68:69], off
	global_load_dwordx4 v[60:63], v[68:69], off offset:64
	global_load_dwordx4 v[64:67], v[68:69], off offset:256
	s_nop 0
	global_load_dwordx4 v[68:71], v[68:69], off offset:320
	v_lshl_add_u64 v[72:73], v[72:73], 0, s[56:57]
	v_lshlrev_b32_e32 v74, 1, v120
	v_mov_b32_e32 v75, v123
	v_lshl_add_u64 v[76:77], v[76:77], 0, s[56:57]
	v_lshl_add_u64 v[80:81], v[80:81], 0, s[58:59]
	v_mov_b32_e32 v147, v123
	v_lshl_add_u64 v[72:73], v[72:73], 0, v[74:75]
	v_lshl_add_u64 v[76:77], v[76:77], 0, v[74:75]
	v_lshl_add_u64 v[80:81], v[80:81], 0, v[146:147]
	global_load_dwordx4 v[72:75], v[72:73], off
	s_nop 0
	global_load_dwordx4 v[76:79], v[76:77], off
	s_add_u32 s8, s16, s56
	global_load_dwordx2 v[158:159], v[80:81], off
	s_addc_u32 s9, s17, 0
	s_add_u32 s8, s8, s58
	s_addc_u32 s9, s9, 0
	v_lshl_add_u64 v[154:155], s[8:9], 0, v[146:147]
	s_and_b32 s8, s3, 0xffffff81
	s_lshl_b32 s44, s55, 2
	s_add_u32 s44, s48, s44
	s_addc_u32 s45, s49, 0
	s_add_u32 s55, s60, s56
	v_lshl_add_u64 v[150:151], v[126:127], 0, s[56:57]
	v_lshl_add_u64 v[152:153], v[134:135], 0, s[56:57]
	s_addc_u32 s56, s61, 0
	s_add_u32 s55, s55, s58
	s_addc_u32 s57, s56, 0
	s_add_u32 s56, s55, s51
	v_or_b32_e32 v80, s8, v133
	s_addc_u32 s57, s57, 0
	v_mov_b32_e32 v149, v123
	v_mov_b32_e32 v122, v123
	v_cmp_eq_u32_e64 s[8:9], 0, v80
	v_lshl_add_u64 v[156:157], s[56:57], 0, v[148:149]
	v_or_b32_e32 v145, s20, v129
	v_lshl_add_u64 v[160:161], v[142:143], 0, s[10:11]
	v_mov_b32_e32 v147, v187
	v_mov_b32_e32 v149, v131
	v_mov_b64_e32 v[162:163], v[122:123]
	v_mov_b64_e32 v[164:165], v[122:123]
	s_mov_b32 s55, s21
	v_mov_b32_e32 v206, 0
	v_mov_b32_e32 v207, 0
	v_mov_b32_e32 v208, 0
	v_mov_b32_e32 v209, 0
	v_mov_b32_e32 v210, 0
	v_mov_b32_e32 v211, 0
	v_mov_b32_e32 v212, 0
	v_mov_b32_e32 v213, 0
	v_and_b32_e32 v243, 15, v130
	v_lshlrev_b32_e32 v214, 4, v243
	v_add_u32_e32 v215, 0x10000, v214
	v_lshrrev_b32_e32 v244, 4, v130
	v_lshrrev_b32_e32 v245, 3, v243
	v_lshl_add_u32 v245, v244, 1, v245
	s_lshl_b32 s91, s68, 3
	v_add_u32_e32 v245, s91, v245
	v_lshlrev_b32_e32 v245, 3, v245
	v_add_u32_e32 v216, 0x1c000, v245
	s_mul_i32 s91, s68, 0x2400
	s_add_i32 s91, s91, 0x14000
	s_cmp_eq_u32 s68, 3
	s_cselect_b32 s91, 0x20800, s91
	v_mul_u32_u24_e32 v218, 0x90, v130
	v_add_u32_e32 v218, s91, v218
	v_mul_u32_u24_e32 v244, 0x90, v244
	v_lshl_add_u32 v244, v243, 3, v244
	v_add_u32_e32 v217, s91, v244
	v_lshrrev_b32_e32 v219, 2, v130
	s_cmp_lt_u32 s3, 0x80
	s_cbranch_scc1 .Lts_rw3
	v_sub_u32_e32 v219, 0, v219

; __device__ __forceinline__ void phase_rwkv_scan(const Fr& F, int jr) {
;     ...
;                 const float inv = 1.f / fmaxf(sqrtf(ss), 1e-12f);
;                 const f32x4 av0 = *(const f32x4*)(Av + p2 * 64 + hk0), av1 = *(const f32x4*)(Av + p2 * 64 + hk0 + 4);
;                 const float av[8] = {av0.x, av0.y, av0.z, av0.w, av1.x, av1.y, av1.z, av1.w};
;                 float o1[8], o2[8], o3[8];
; #pragma unroll
;                 for (int i = 0; i < 8; ++i) { const float kkv = kq[i] * inv; o1[i] = kkv; o2[i] = kkv * av[i]; o3[i] = kr[i] * (1.f + (av[i] - 1.f) * kac[i]); }
;                 const int o = p2 * 64 + hk0;
;                 *(f32x4*)(KK + o) = (f32x4){o1[0], o1[1], o1[2], o1[3]}; *(f32x4*)(KK + o + 4) = (f32x4){o1[4], o1[5], o1[6], o1[7]};
;                 *(f32x4*)(Bv + o) = (f32x4){o2[0], o2[1], o2[2], o2[3]}; *(f32x4*)(Bv + o + 4) = (f32x4){o2[4], o2[5], o2[6], o2[7]};
;                 *(f32x4*)(KD + o) = (f32x4){o3[0], o3[1], o3[2], o3[3]}; *(f32x4*)(KD + o + 4) = (f32x4){o3[4], o3[5], o3[6], o3[7]};
;                 *(f32x4*)(Rr + o) = (f32x4){rr[0], rr[1], rr[2], rr[3]}; *(f32x4*)(Rr + o + 4) = (f32x4){rr[4], rr[5], rr[6], rr[7]};
;                 *(f32x4*)(Vv + p2 * 32 + 4 * j8) = (f32x4){lo_bf(vw.x), hi_bf(vw.x), lo_bf(vw.y), hi_bf(vw.y)};
;             }
;             if (chunk + 1 < TB / 64) {
;                 const size_t row1 = (size_t)b * TB + tokof(s, (chunk + 1) * 64 + p1), row2 = (size_t)b * TB + tokof(s, (chunk + 1) * 64 + p2);
; #pragma unroll
;                 for (int kst = 0; kst < 2; ++kst) { Aw[kst] = *(const bf16x8*)(LM + row1 * 256 + 64 * s + 32 * kst + 8 * lq); Aa[kst] = *(const bf16x8*)(LM + row1 * 256 + 128 + 64 * s + 32 * kst + 8 * lq); }
;                 kw = *(const u32x4*)(Kb + row2 * D + h * 64 + hk0); rw = *(const u32x4*)(Rb + row2 * D + h * 64 + hk0); vw = *(const u32x2*)(Vb + row2 * D + h * 64 + 32 * half + 4 * j8);
;             }
.LBB0_2536:
	s_or_b64 exec, exec, s[10:11]
	v_add_f32_e32 v104, v104, v105
	v_mul_f32_e32 v105, 0x4f800000, v104
	v_cmp_gt_f32_e32 vcc, s52, v104
	s_nop 1
	v_cndmask_b32_e32 v104, v104, v105, vcc
	v_sqrt_f32_e32 v105, v104
	s_nop 0
	v_add_u32_e32 v106, -1, v105
	v_fma_f32 v108, -v106, v105, v104
	v_add_u32_e32 v107, 1, v105
	v_cmp_ge_f32_e64 s[10:11], 0, v108
	s_nop 1
	v_cndmask_b32_e64 v106, v105, v106, s[10:11]
	v_fma_f32 v105, -v107, v105, v104
	v_cmp_lt_f32_e64 s[10:11], 0, v105
	s_nop 1
	v_cndmask_b32_e64 v105, v106, v107, s[10:11]
	v_mul_f32_e32 v106, 0x37800000, v105
	v_cndmask_b32_e32 v105, v105, v106, vcc
	v_cmp_class_f32_e32 vcc, v104, v188
	s_nop 1
	v_cndmask_b32_e32 v104, v105, v104, vcc
	v_max_f32_e32 v104, 0x2b8cbccc, v104
	v_div_scale_f32 v105, s[10:11], v104, v104, 1.0
	v_rcp_f32_e32 v106, v105
	s_add_i32 s10, s55, 1
	s_cmpk_eq_i32 s55, 0x43
	v_fma_f32 v107, -v105, v106, 1.0
	v_fmac_f32_e32 v106, v107, v106
	v_div_scale_f32 v107, vcc, 1.0, v104, 1.0
	v_mul_f32_e32 v108, v107, v106
	v_fma_f32 v109, -v105, v108, v107
	v_fmac_f32_e32 v108, v109, v106
	v_fma_f32 v105, -v105, v108, v107
	v_div_fmas_f32 v105, v105, v106, v108
	v_div_fixup_f32 v112, v105, v104, 1.0
	ds_read_b128 v[104:107], v169
	ds_read_b128 v[108:111], v169 offset:16
	v_pk_mul_f32 v[96:97], v[96:97], v[112:113] op_sel_hi:[1,0]
	v_pk_mul_f32 v[98:99], v[98:99], v[112:113] op_sel_hi:[1,0]
	v_pk_mul_f32 v[100:101], v[100:101], v[112:113] op_sel_hi:[1,0]
	v_pk_mul_f32 v[102:103], v[102:103], v[112:113] op_sel_hi:[1,0]
	ds_write_b128 v170, v[96:99] offset:16384
	ds_write_b128 v170, v[100:103] offset:16400
	s_waitcnt lgkmcnt(3)
	v_pk_mul_f32 v[98:99], v[98:99], v[106:107]
	v_pk_mul_f32 v[96:97], v[96:97], v[104:105]
	ds_write_b128 v170, v[96:99] offset:32768
	s_waitcnt lgkmcnt(3)
	v_pk_mul_f32 v[98:99], v[102:103], v[110:111]
	v_pk_mul_f32 v[96:97], v[100:101], v[108:109]
	ds_write_b128 v170, v[96:99] offset:32784
	v_pk_add_f32 v[96:97], v[106:107], -1.0 op_sel_hi:[1,0]
	v_pk_add_f32 v[98:99], v[104:105], -1.0 op_sel_hi:[1,0]
	v_pk_fma_f32 v[96:97], v[54:55], v[96:97], 1.0 op_sel_hi:[1,1,0]
	v_pk_fma_f32 v[100:101], v[52:53], v[98:99], 1.0 op_sel_hi:[1,1,0]
	v_pk_mul_f32 v[98:99], v[96:97], v[92:93]
	v_pk_mul_f32 v[96:97], v[100:101], v[88:89]
	v_pk_add_f32 v[88:89], v[110:111], -1.0 op_sel_hi:[1,0]
	v_pk_add_f32 v[92:93], v[108:109], -1.0 op_sel_hi:[1,0]
	ds_write_b128 v170, v[96:99] offset:49152
	v_pk_fma_f32 v[88:89], v[50:51], v[88:89], 1.0 op_sel_hi:[1,1,0]
	v_pk_fma_f32 v[96:97], v[48:49], v[92:93], 1.0 op_sel_hi:[1,1,0]
	v_pk_mul_f32 v[92:93], v[88:89], v[94:95]
	v_pk_mul_f32 v[90:91], v[96:97], v[90:91]
	ds_write_b128 v170, v[90:93] offset:49168
	ds_write_b128 v171, v[84:87]
	ds_write_b128 v171, v[80:83] offset:16
	s_waitcnt vmcnt(0)
	v_lshlrev_b32_e32 v80, 16, v158
	v_and_b32_e32 v81, 0xffff0000, v158
	v_mov_b32_e32 v82, v81
	v_mov_b32_e32 v83, v80
	ds_write_b128 v221, v[80:83]
	v_lshlrev_b32_e32 v84, 16, v159
	v_and_b32_e32 v85, 0xffff0000, v159
	v_mov_b32_e32 v86, v85
	v_mov_b32_e32 v87, v84
	ds_write_b128 v221, v[84:87] offset:16
	s_cbranch_scc1 .LBB0_2538
	s_lshl_b32 s11, s10, 6
	s_cmp_gt_u32 s55, 2
	v_or_b32_e32 v56, s11, v121
	s_cselect_b32 s55, s53, 0xff
	v_add_u32_e32 v58, s11, v129
	v_sub_u32_e32 v57, s55, v56
	v_cmp_lt_u32_e32 vcc, s37, v58
	v_cndmask_b32_e64 v56, v57, v56, s[6:7]
	v_ashrrev_i32_e32 v57, 31, v56
	v_cndmask_b32_e32 v59, v137, v191, vcc
	v_sub_u32_e32 v59, v59, v58
	v_lshl_add_u64 v[56:57], v[56:57], 0, s[20:21]
	v_cndmask_b32_e64 v72, v59, v58, s[6:7]
	v_ashrrev_i32_e32 v73, 31, v72
	v_lshlrev_b64 v[56:57], 9, v[56:57]
	v_lshl_add_u64 v[68:69], v[160:161], 0, v[56:57]
	v_lshl_add_u64 v[72:73], v[72:73], 0, s[20:21]
	global_load_dwordx4 v[56:59], v[68:69], off
	global_load_dwordx4 v[60:63], v[68:69], off offset:64
	global_load_dwordx4 v[64:67], v[68:69], off offset:256
	s_nop 0
	global_load_dwordx4 v[68:71], v[68:69], off offset:320
	v_lshlrev_b64 v[80:81], 11, v[72:73]
	v_lshl_add_u64 v[72:73], v[150:151], 0, v[80:81]
	v_lshl_add_u64 v[76:77], v[152:153], 0, v[80:81]
	v_lshl_add_u64 v[80:81], v[154:155], 0, v[80:81]
	global_load_dwordx4 v[72:75], v[72:73], off
	s_nop 0
	global_load_dwordx4 v[76:79], v[76:77], off
	s_nop 0
	global_load_dwordx2 v[158:159], v[80:81], off

; #define LDS_BAR() asm volatile("s_waitcnt lgkmcnt(0)\n\ts_barrier" ::: "memory")
; __device__ __forceinline__ void phase_rwkv_scan(const Fr& F, int jr) {
;     ...
;             LDS_BAR();
;         }
;         LDS_BAR();
;     }
.Lrw3_skip:
	s_waitcnt lgkmcnt(0)
	s_barrier
	v_add_u32_e32 v149, 64, v149
	v_subrev_u32_e32 v147, 64, v147
	s_cmpk_eq_i32 s10, 0x44
	s_mov_b32 s55, s10
	s_cbranch_scc0 .LBB0_2534
	s_waitcnt lgkmcnt(0)
	s_barrier
	s_add_i32 s3, s3, s30
	s_cmpk_gt_i32 s3, 0xff
	s_cbranch_scc0 .LBB0_2533

; __global__ void __launch_bounds__(NTHR) fwd_kernel(Args args) {
;     extern __shared__ __attribute__((aligned(16))) unsigned char lds[];
;     cg::grid_group grid = cg::this_grid();
;     Fr F; F.a = &args; F.lds = lds; F.ws = args.ws; F.tid = threadIdx.x; F.lane = F.tid & 63; F.wave = __builtin_amdgcn_readfirstlane(F.tid >> 6); F.gw = blockIdx.x * NWAVES + F.wave;
	.amdhsa_kernel _Z10fwd_kernel4Args
		.amdhsa_group_segment_fixed_size 0
		.amdhsa_private_segment_fixed_size 0
		.amdhsa_kernarg_size 584
		.amdhsa_user_sgpr_count 2
		.amdhsa_user_sgpr_dispatch_ptr 0
		.amdhsa_user_sgpr_queue_ptr 0
		.amdhsa_user_sgpr_kernarg_segment_ptr 1
		.amdhsa_user_sgpr_dispatch_id 0
		.amdhsa_user_sgpr_kernarg_preload_length 0
		.amdhsa_user_sgpr_kernarg_preload_offset 0
		.amdhsa_user_sgpr_private_segment_size 0
		.amdhsa_uses_dynamic_stack 0
		.amdhsa_enable_private_segment 0
		.amdhsa_system_sgpr_workgroup_id_x 1
		.amdhsa_system_sgpr_workgroup_id_y 0
		.amdhsa_system_sgpr_workgroup_id_z 0
		.amdhsa_system_sgpr_workgroup_info 0
		.amdhsa_system_vgpr_workitem_id 2
		.amdhsa_next_free_vgpr 246
		.amdhsa_next_free_sgpr 96
		.amdhsa_accum_offset 248
		.amdhsa_reserve_vcc 1
		.amdhsa_float_round_mode_32 0
		.amdhsa_float_round_mode_16_64 0
		.amdhsa_float_denorm_mode_32 3
		.amdhsa_float_denorm_mode_16_64 3
		.amdhsa_dx10_clamp 1
		.amdhsa_ieee_mode 1
		.amdhsa_fp16_overflow 0
		.amdhsa_tg_split 0
		.amdhsa_exception_fp_ieee_invalid_op 0
		.amdhsa_exception_fp_denorm_src 0
		.amdhsa_exception_fp_ieee_div_zero 0
		.amdhsa_exception_fp_ieee_overflow 0
		.amdhsa_exception_fp_ieee_underflow 0
		.amdhsa_exception_fp_ieee_inexact 0
		.amdhsa_exception_int_div_zero 0
	.end_amdhsa_kernel

; __global__ void __launch_bounds__(NTHR) fwd_kernel(Args args) {
;     extern __shared__ __attribute__((aligned(16))) unsigned char lds[];
;     cg::grid_group grid = cg::this_grid();
;     Fr F; F.a = &args; F.lds = lds; F.ws = args.ws; F.tid = threadIdx.x; F.lane = F.tid & 63; F.wave = __builtin_amdgcn_readfirstlane(F.tid >> 6); F.gw = blockIdx.x * NWAVES + F.wave;
amdhsa.kernels:
  - .agpr_count:     0
    .args:
      - .offset:         0
        .size:           328
        .value_kind:     by_value
      - .offset:         328
        .size:           4
        .value_kind:     hidden_block_count_x
      - .offset:         332
        .size:           4
        .value_kind:     hidden_block_count_y
      - .offset:         336
        .size:           4
        .value_kind:     hidden_block_count_z
      - .offset:         340
        .size:           2
        .value_kind:     hidden_group_size_x
      - .offset:         342
        .size:           2
        .value_kind:     hidden_group_size_y
      - .offset:         344
        .size:           2
        .value_kind:     hidden_group_size_z
      - .offset:         346
        .size:           2
        .value_kind:     hidden_remainder_x
      - .offset:         348
        .size:           2
        .value_kind:     hidden_remainder_y
      - .offset:         350
        .size:           2
        .value_kind:     hidden_remainder_z
      - .offset:         368
        .size:           8
        .value_kind:     hidden_global_offset_x
      - .offset:         376
        .size:           8
        .value_kind:     hidden_global_offset_y
      - .offset:         384
        .size:           8
        .value_kind:     hidden_global_offset_z
      - .offset:         392
        .size:           2
        .value_kind:     hidden_grid_dims
      - .offset:         416
        .size:           8
        .value_kind:     hidden_multigrid_sync_arg
      - .offset:         448
        .size:           4
        .value_kind:     hidden_dynamic_lds_size
    .group_segment_fixed_size: 0
    .kernarg_segment_align: 8
    .kernarg_segment_size: 584
    .language:       OpenCL C
    .language_version:
      - 2
      - 0
    .max_flat_workgroup_size: 512
    .name:           _Z10fwd_kernel4Args
    .private_segment_fixed_size: 0
    .sgpr_count:     102
    .sgpr_spill_count: 0
    .symbol:         _Z10fwd_kernel4Args.kd
    .uniform_work_group_size: 1
    .uses_dynamic_stack: false
    .vgpr_count:     246
    .vgpr_spill_count: 0
    .wavefront_size: 64
